# strategy 7: DPP quad_perm / row_half_mirror / row_mirror adds replace the intra-row ds_bpermute round trips of the xor-butterfly sums (RMSNorm x3, gdn_norm, gdn_prep l2norm)
# baseline (speedup 1.0000x reference)
; __device__ __forceinline__ unsigned cvt_pk_bf16(float lo, float hi) { f32x2 v = {lo, hi}; bf16x2_t r = __builtin_convertvector(v, bf16x2_t); return __builtin_bit_cast(unsigned, r); }
; __device__ __forceinline__ void phase_g(KA a, int layer, const float* x1, unsigned char* lds, const int tid_, const int bid_) {
;     ...
;     for (int m = gw; m < T_; m += NGW) {
;         const f32x4* xr = (const f32x4*)(x1 + (size_t)m * D_) + lane;
;         f32x4 v[8]; float ss = 0.f;
; #pragma unroll
;         for (int j = 0; j < 8; ++j) { v[j] = xr[64 * j]; ss += (v[j].x * v[j].x + v[j].y * v[j].y) + (v[j].z * v[j].z + v[j].w * v[j].w); }
;         ss = wave_sum(ss);
;         const float rstd = rsqrtf(ss * (1.0f / D_) + 1e-6f);
;         u32x2* o8 = (u32x2*)(H + (size_t)m * D_) + lane;
; #pragma unroll
;         for (int j = 0; j < 8; ++j) { v[j] = v[j] * rstd * gn[j]; u32x2 w; w.x = cvt_pk_bf16(v[j].x, v[j].y); w.y = cvt_pk_bf16(v[j].z, v[j].w); o8[64 * j] = w; }
;     }
.LBB0_50:
	global_load_dwordx4 v[38:41], v[44:45], off offset:-4096
	global_load_dwordx4 v[34:37], v[44:45], off offset:-3072
	global_load_dwordx4 v[56:59], v[44:45], off offset:-2048
	global_load_dwordx4 v[60:63], v[44:45], off offset:-1024
	global_load_dwordx4 v[64:67], v[44:45], off
	global_load_dwordx4 v[68:71], v[44:45], off offset:1024
	global_load_dwordx4 v[72:75], v[44:45], off offset:2048
	global_load_dwordx4 v[76:79], v[44:45], off offset:3072
	v_add_u32_e32 v42, s8, v42
	s_waitcnt vmcnt(6)
	v_mov_b32_e32 v158, v39
	v_mov_b32_e32 v159, v35
	v_mov_b32_e32 v156, v38
	v_mov_b32_e32 v157, v34
	v_pk_mul_f32 v[158:159], v[158:159], v[158:159]
	v_mov_b32_e32 v160, v41
	v_mov_b32_e32 v161, v37
	v_pk_fma_f32 v[156:157], v[156:157], v[156:157], v[158:159]
	v_mov_b32_e32 v158, v40
	v_mov_b32_e32 v159, v36
	v_pk_mul_f32 v[160:161], v[160:161], v[160:161]
	s_nop 0
	v_pk_fma_f32 v[158:159], v[158:159], v[158:159], v[160:161]
	s_nop 0
	v_pk_add_f32 v[168:169], v[156:157], v[158:159]
	v_pk_add_f32 v[168:169], v[168:169], v[168:169] op_sel:[0,1] op_sel_hi:[1,0]
	s_waitcnt vmcnt(5)
	v_pk_mul_f32 v[160:161], v[58:59], v[58:59]
	v_pk_mul_f32 v[162:163], v[56:57], v[56:57]
	s_nop 0
	v_pk_mov_b32 v[164:165], v[162:163], v[160:161] op_sel:[1,0]
	v_mov_b32_e32 v163, v161
	v_pk_add_f32 v[170:171], v[164:165], v[162:163]
	v_pk_add_f32 v[170:171], v[170:171], v[170:171] op_sel:[0,1] op_sel_hi:[1,0]
	s_waitcnt vmcnt(3)
	v_mul_f32_e32 v0, v64, v64
	v_mul_f32_e32 v43, v65, v65
	v_mov_b32_e32 v169, v0
	v_mov_b32_e32 v171, v43
	v_mul_f32_e32 v0, v61, v61
	v_pk_add_f32 v[168:169], v[168:169], v[170:171]
	v_pk_fma_f32 v[170:171], v[60:61], v[60:61], v[0:1] op_sel_hi:[1,1,0]
	v_mul_f32_e32 v0, v63, v63
	v_mul_f32_e32 v48, v66, v66
	v_mul_f32_e32 v55, v67, v67
	v_pk_fma_f32 v[172:173], v[62:63], v[62:63], v[0:1] op_sel_hi:[1,1,0]
	v_mov_b32_e32 v171, v48
	v_mov_b32_e32 v173, v55
	v_pk_add_f32 v[170:171], v[170:171], v[172:173]
	s_nop 0
	v_pk_add_f32 v[80:81], v[168:169], v[170:171]
	v_pk_add_f32 v[80:81], v[80:81], v[80:81] op_sel:[0,1] op_sel_hi:[1,0]
	s_waitcnt vmcnt(2)
	v_pk_mul_f32 v[172:173], v[70:71], v[70:71]
	v_pk_mul_f32 v[174:175], v[68:69], v[68:69]
	s_nop 0
	v_pk_mov_b32 v[176:177], v[174:175], v[172:173] op_sel:[1,0]
	v_mov_b32_e32 v175, v173
	v_pk_add_f32 v[82:83], v[176:177], v[174:175]
	v_pk_add_f32 v[82:83], v[82:83], v[82:83] op_sel:[0,1] op_sel_hi:[1,0]
	v_lshl_add_u64 v[44:45], v[44:45], 0, s[12:13]
	s_waitcnt vmcnt(0)
	v_mul_f32_e32 v0, v76, v76
	v_mul_f32_e32 v43, v77, v77
	v_mov_b32_e32 v81, v0
	v_mov_b32_e32 v83, v43
	v_mul_f32_e32 v0, v73, v73
	v_pk_add_f32 v[80:81], v[80:81], v[82:83]
	v_pk_fma_f32 v[82:83], v[72:73], v[72:73], v[0:1] op_sel_hi:[1,1,0]
	v_mul_f32_e32 v0, v75, v75
	v_mul_f32_e32 v48, v78, v78
	v_mul_f32_e32 v55, v79, v79
	v_pk_fma_f32 v[84:85], v[74:75], v[74:75], v[0:1] op_sel_hi:[1,1,0]
	v_mov_b32_e32 v83, v48
	v_mov_b32_e32 v85, v55
	v_pk_add_f32 v[82:83], v[82:83], v[84:85]
	s_nop 0
	v_pk_add_f32 v[80:81], v[80:81], v[82:83]
	s_nop 0
	v_add_f32_e32 v0, v80, v81
	s_nop 1
	v_add_f32_dpp v0, v0, v0 quad_perm:[1,0,3,2] row_mask:0xf bank_mask:0xf
	s_waitcnt lgkmcnt(0)
	s_nop 1
	v_add_f32_dpp v0, v0, v0 quad_perm:[2,3,0,1] row_mask:0xf bank_mask:0xf
	s_waitcnt lgkmcnt(0)
	s_nop 1
	v_add_f32_dpp v0, v0, v0 row_half_mirror row_mask:0xf bank_mask:0xf
	s_waitcnt lgkmcnt(0)
	s_nop 1
	v_add_f32_dpp v0, v0, v0 row_mirror row_mask:0xf bank_mask:0xf
	s_waitcnt lgkmcnt(0)
	ds_bpermute_b32 v43, v53, v0
	s_waitcnt lgkmcnt(0)
	v_add_f32_e32 v0, v0, v43
	ds_bpermute_b32 v43, v54, v0
	s_waitcnt lgkmcnt(0)
	v_add_f32_e32 v0, v0, v43
	v_fmamk_f32 v0, v0, 0x3a000000, v227
	v_cmp_gt_f32_e32 vcc, s24, v0
	v_mul_f32_e32 v43, 0x4b800000, v0
	s_nop 0
	v_cndmask_b32_e32 v0, v0, v43, vcc
	v_rsq_f32_e32 v0, v0
	s_nop 0
	v_mul_f32_e32 v43, 0x45800000, v0
	v_cndmask_b32_e32 v0, v0, v43, vcc
	v_pk_mul_f32 v[34:35], v[34:35], v[0:1] op_sel_hi:[1,0]
	v_pk_mul_f32 v[36:37], v[36:37], v[0:1] op_sel_hi:[1,0]
	v_pk_mul_f32 v[34:35], v[6:7], v[34:35]
	v_pk_mul_f32 v[36:37], v[8:9], v[36:37]
	v_cvt_pk_bf16_f32 v34, v34, v35
	v_cvt_pk_bf16_f32 v35, v36, v37
	global_store_dwordx2 v[46:47], v[34:35], off offset:-3072
	v_pk_mul_f32 v[34:35], v[56:57], v[0:1] op_sel_hi:[1,0]
	v_pk_mul_f32 v[36:37], v[58:59], v[0:1] op_sel_hi:[1,0]
	v_pk_mul_f32 v[34:35], v[10:11], v[34:35]
	v_pk_mul_f32 v[36:37], v[12:13], v[36:37]
	v_cvt_pk_bf16_f32 v34, v34, v35
	v_cvt_pk_bf16_f32 v35, v36, v37
	global_store_dwordx2 v[46:47], v[34:35], off offset:-2560
	v_pk_mul_f32 v[34:35], v[60:61], v[0:1] op_sel_hi:[1,0]
	v_pk_mul_f32 v[36:37], v[62:63], v[0:1] op_sel_hi:[1,0]
	v_pk_mul_f32 v[34:35], v[14:15], v[34:35]
	v_pk_mul_f32 v[36:37], v[16:17], v[36:37]
	v_cvt_pk_bf16_f32 v34, v34, v35
	v_cvt_pk_bf16_f32 v35, v36, v37
	global_store_dwordx2 v[46:47], v[34:35], off offset:-2048
	v_pk_mul_f32 v[34:35], v[64:65], v[0:1] op_sel_hi:[1,0]
	v_pk_mul_f32 v[36:37], v[66:67], v[0:1] op_sel_hi:[1,0]
	v_pk_mul_f32 v[34:35], v[18:19], v[34:35]
	v_pk_mul_f32 v[36:37], v[20:21], v[36:37]
	v_cvt_pk_bf16_f32 v34, v34, v35
	v_cvt_pk_bf16_f32 v35, v36, v37
	global_store_dwordx2 v[46:47], v[34:35], off offset:-1536
	v_pk_mul_f32 v[34:35], v[68:69], v[0:1] op_sel_hi:[1,0]
	v_pk_mul_f32 v[36:37], v[70:71], v[0:1] op_sel_hi:[1,0]
	v_pk_mul_f32 v[34:35], v[22:23], v[34:35]
	v_pk_mul_f32 v[36:37], v[24:25], v[36:37]
	v_cvt_pk_bf16_f32 v34, v34, v35
	v_cvt_pk_bf16_f32 v35, v36, v37
	global_store_dwordx2 v[46:47], v[34:35], off offset:-1024
	v_pk_mul_f32 v[34:35], v[72:73], v[0:1] op_sel_hi:[1,0]
	v_pk_mul_f32 v[36:37], v[74:75], v[0:1] op_sel_hi:[1,0]
	v_pk_mul_f32 v[34:35], v[26:27], v[34:35]
	v_pk_mul_f32 v[36:37], v[28:29], v[36:37]
	v_cvt_pk_bf16_f32 v34, v34, v35
	v_cvt_pk_bf16_f32 v35, v36, v37
	v_pk_mul_f32 v[38:39], v[38:39], v[0:1] op_sel_hi:[1,0]
	v_pk_mul_f32 v[40:41], v[40:41], v[0:1] op_sel_hi:[1,0]
	global_store_dwordx2 v[46:47], v[34:35], off offset:-512
	v_pk_mul_f32 v[34:35], v[76:77], v[0:1] op_sel_hi:[1,0]
	v_pk_mul_f32 v[36:37], v[78:79], v[0:1] op_sel_hi:[1,0]
	v_pk_mul_f32 v[40:41], v[4:5], v[40:41]
	v_pk_mul_f32 v[38:39], v[2:3], v[38:39]
	v_pk_mul_f32 v[36:37], v[32:33], v[36:37]
	v_pk_mul_f32 v[34:35], v[30:31], v[34:35]
	v_cvt_pk_bf16_f32 v38, v38, v39
	v_cvt_pk_bf16_f32 v39, v40, v41
	v_cvt_pk_bf16_f32 v34, v34, v35
	v_cvt_pk_bf16_f32 v35, v36, v37
	v_cmp_lt_i32_e32 vcc, s22, v42
	global_store_dwordx2 v[46:47], v[38:39], off offset:-3584
	global_store_dwordx2 v[46:47], v[34:35], off
	v_lshl_add_u64 v[46:47], v[46:47], 0, s[14:15]
	s_or_b64 s[16:17], vcc, s[16:17]
	s_andn2_b64 exec, exec, s[16:17]
	s_cbranch_execnz .LBB0_50

; __device__ __forceinline__ void unpack8(const u32x4 w, float* f) { f[0] = bflo(w.x); f[1] = bfhi(w.x); f[2] = bflo(w.y); f[3] = bfhi(w.y); f[4] = bflo(w.z); f[5] = bfhi(w.z); f[6] = bflo(w.w); f[7] = bfhi(w.w); }
; __device__ __forceinline__ u32x4 pack8(const float* f) { u32x4 w; w.x = cvt_pk_bf16(f[0], f[1]); w.y = cvt_pk_bf16(f[2], f[3]); w.z = cvt_pk_bf16(f[4], f[5]); w.w = cvt_pk_bf16(f[6], f[7]); return w; }
; __device__ __forceinline__ float siluf_(float x) { return x * sigmoidf_(x); }
; __device__ __forceinline__ void gdn_norm(KA a, int layer, const int tid_, const int bid_) {
;     ...
;     for (int item = bid_; item < 2048; item += gridDim.x) {
;         const int c = item >> 3, h = item & 7;
;         const size_t go = (size_t)(c * 64 + tl) * 1024 + h * 128 + 16 * sub;
;         float o[16], zf[16]; float ms = 0.f;
;         { const u32x4 o0 = *(const u32x4*)((const bf16_t*)(ws + WS_ORAW) + go), o1 = *(const u32x4*)((const bf16_t*)(ws + WS_ORAW) + go + 8); unpack8(o0, o); unpack8(o1, o + 8); }
; #pragma unroll
;         for (int e = 0; e < 16; ++e) ms += o[e] * o[e];
;         ms += __shfl_xor(ms, 1); ms += __shfl_xor(ms, 2); ms += __shfl_xor(ms, 4);
;         const float r = rsqrtf(ms * (1.0f / 128.0f) + 1e-6f);
;         { const u32x4 z0 = *(const u32x4*)((const bf16_t*)(ws + WS_Z) + go), z1 = *(const u32x4*)((const bf16_t*)(ws + WS_Z) + go + 8); unpack8(z0, zf); unpack8(z1, zf + 8); }
; #pragma unroll
;         for (int e = 0; e < 16; ++e) o[e] = o[e] * r * ng[e] * siluf_(zf[e]);
;         bf16_t* dst = (bf16_t*)(ws + WS_OG) + go;
;         *(u32x4*)dst = pack8(o); *(u32x4*)(dst + 8) = pack8(o + 8);
;     }
.LBB0_131:
	s_and_b32 s21, s18, 0xffffffc0
	v_add_u32_e32 v4, s21, v130
	v_ashrrev_i32_e32 v5, 31, v4
	v_lshlrev_b64 v[4:5], 10, v[4:5]
	s_and_b32 s21, s16, 0x380
	v_or_b32_e32 v4, s21, v4
	v_or_b32_e32 v4, v4, v131
	v_lshlrev_b64 v[4:5], 1, v[4:5]
	v_lshl_add_u64 v[6:7], s[10:11], 0, v[4:5]
	global_load_dwordx4 v[18:21], v[6:7], off
	global_load_dwordx4 v[22:25], v[6:7], off offset:16
	v_lshl_add_u64 v[6:7], s[12:13], 0, v[4:5]
	global_load_dwordx4 v[26:29], v[6:7], off
	global_load_dwordx4 v[30:33], v[6:7], off offset:16
	v_lshl_add_u64 v[4:5], s[14:15], 0, v[4:5]
	s_add_i32 s20, s20, s7
	s_add_i32 s16, s16, s17
	s_add_i32 s18, s18, s19
	s_cmpk_lt_i32 s20, 0x800
	s_waitcnt vmcnt(0)
	v_lshlrev_b32_e32 v12, 16, v24
	v_lshlrev_b32_e32 v64, 16, v29
	v_lshlrev_b32_e32 v6, 16, v33
	v_mul_f32_e32 v7, 0xbfb8aa3b, v6
	v_exp_f32_e32 v7, v7
	v_lshlrev_b32_e32 v50, 16, v32
	v_and_b32_e32 v51, 0xffff0000, v32
	v_lshlrev_b32_e32 v56, 16, v31
	v_add_f32_e32 v7, 1.0, v7
	v_rcp_f32_e32 v7, v7
	v_and_b32_e32 v57, 0xffff0000, v31
	v_lshlrev_b32_e32 v60, 16, v30
	v_and_b32_e32 v61, 0xffff0000, v30
	v_mul_f32_e32 v6, v7, v6
	v_mul_f32_e32 v7, 0xbfb8aa3b, v50
	v_exp_f32_e32 v7, v7
	v_and_b32_e32 v65, 0xffff0000, v29
	v_lshlrev_b32_e32 v68, 16, v28
	v_and_b32_e32 v10, 0xffff0000, v33
	v_add_f32_e32 v7, 1.0, v7
	v_rcp_f32_e32 v52, v7
	v_mul_f32_e32 v7, 0xbfb8aa3b, v51
	v_exp_f32_e32 v7, v7
	global_load_dwordx4 v[32:35], v[2:3], off offset:48
	global_load_dwordx4 v[36:39], v[2:3], off offset:32
	global_load_dwordx4 v[40:43], v[2:3], off offset:16
	global_load_dwordx4 v[44:47], v[2:3], off
	v_and_b32_e32 v69, 0xffff0000, v28
	v_lshlrev_b32_e32 v72, 16, v27
	v_add_f32_e32 v7, 1.0, v7
	v_rcp_f32_e32 v53, v7
	v_mul_f32_e32 v7, 0xbfb8aa3b, v56
	v_exp_f32_e32 v7, v7
	v_and_b32_e32 v73, 0xffff0000, v27
	v_lshlrev_b32_e32 v76, 16, v26
	v_and_b32_e32 v77, 0xffff0000, v26
	v_add_f32_e32 v7, 1.0, v7
	v_rcp_f32_e32 v58, v7
	v_mul_f32_e32 v7, 0xbfb8aa3b, v57
	v_exp_f32_e32 v7, v7
	v_pk_mul_f32 v[50:51], v[52:53], v[50:51]
	v_lshlrev_b32_e32 v52, 16, v23
	v_and_b32_e32 v53, 0xffff0000, v23
	v_add_f32_e32 v7, 1.0, v7
	v_rcp_f32_e32 v59, v7
	v_mul_f32_e32 v7, 0xbfb8aa3b, v60
	v_exp_f32_e32 v7, v7
	v_pk_mul_f32 v[54:55], v[52:53], v[52:53]
	v_pk_mul_f32 v[56:57], v[58:59], v[56:57]
	v_lshlrev_b32_e32 v58, 16, v22
	v_add_f32_e32 v7, 1.0, v7
	v_rcp_f32_e32 v30, v7
	v_mul_f32_e32 v7, 0xbfb8aa3b, v61
	v_exp_f32_e32 v7, v7
	v_and_b32_e32 v59, 0xffff0000, v22
	v_pk_mul_f32 v[22:23], v[58:59], v[58:59]
	v_and_b32_e32 v13, 0xffff0000, v24
	v_add_f32_e32 v7, 1.0, v7
	v_rcp_f32_e32 v31, v7
	v_mul_f32_e32 v7, 0xbfb8aa3b, v64
	v_exp_f32_e32 v7, v7
	v_lshlrev_b32_e32 v9, 16, v25
	v_pk_mul_f32 v[30:31], v[30:31], v[60:61]
	v_lshlrev_b32_e32 v60, 16, v21
	v_add_f32_e32 v7, 1.0, v7
	v_rcp_f32_e32 v66, v7
	v_mul_f32_e32 v7, 0xbfb8aa3b, v65
	v_exp_f32_e32 v7, v7
	v_and_b32_e32 v61, 0xffff0000, v21
	v_pk_mul_f32 v[62:63], v[60:61], v[60:61]
	v_and_b32_e32 v11, 0xffff0000, v25
	v_add_f32_e32 v7, 1.0, v7
	v_rcp_f32_e32 v67, v7
	v_mul_f32_e32 v7, 0xbfb8aa3b, v68
	v_exp_f32_e32 v7, v7
	v_pk_mul_f32 v[24:25], v[12:13], v[12:13]
	v_pk_mul_f32 v[64:65], v[66:67], v[64:65]
	v_lshlrev_b32_e32 v66, 16, v20
	v_add_f32_e32 v7, 1.0, v7
	v_rcp_f32_e32 v28, v7
	v_mul_f32_e32 v7, 0xbfb8aa3b, v69
	v_exp_f32_e32 v7, v7
	v_and_b32_e32 v67, 0xffff0000, v20
	v_pk_mul_f32 v[20:21], v[66:67], v[66:67]
	v_mov_b32_e32 v8, v11
	v_add_f32_e32 v7, 1.0, v7
	v_rcp_f32_e32 v29, v7
	v_mul_f32_e32 v7, 0xbfb8aa3b, v72
	v_exp_f32_e32 v7, v7
	v_pk_mul_f32 v[48:49], v[8:9], v[8:9]
	v_pk_mul_f32 v[28:29], v[28:29], v[68:69]
	v_lshlrev_b32_e32 v68, 16, v19
	v_add_f32_e32 v7, 1.0, v7
	v_rcp_f32_e32 v74, v7
	v_mul_f32_e32 v7, 0xbfb8aa3b, v73
	v_exp_f32_e32 v7, v7
	v_and_b32_e32 v69, 0xffff0000, v19
	v_pk_mul_f32 v[70:71], v[68:69], v[68:69]
	v_add_f32_e32 v7, 1.0, v7
	v_rcp_f32_e32 v75, v7
	v_mul_f32_e32 v7, 0xbfb8aa3b, v76
	v_exp_f32_e32 v7, v7
	v_pk_mul_f32 v[72:73], v[74:75], v[72:73]
	v_lshlrev_b32_e32 v74, 16, v18
	v_add_f32_e32 v7, 1.0, v7
	v_rcp_f32_e32 v26, v7
	v_mul_f32_e32 v7, 0xbfb8aa3b, v77
	v_exp_f32_e32 v7, v7
	v_and_b32_e32 v75, 0xffff0000, v18
	v_pk_mul_f32 v[18:19], v[74:75], v[74:75]
	v_add_f32_e32 v7, 1.0, v7
	v_rcp_f32_e32 v27, v7
	v_add_f32_e32 v7, v18, v19
	v_add_f32_e32 v7, v70, v7
	v_add_f32_e32 v7, v71, v7
	v_add_f32_e32 v7, v20, v7
	v_add_f32_e32 v7, v21, v7
	v_add_f32_e32 v7, v62, v7
	v_add_f32_e32 v7, v63, v7
	v_add_f32_e32 v7, v22, v7
	v_add_f32_e32 v7, v23, v7
	v_add_f32_e32 v7, v54, v7
	v_add_f32_e32 v7, v55, v7
	v_add_f32_e32 v7, v24, v7
	v_add_f32_e32 v7, v25, v7
	v_add_f32_e32 v7, v49, v7
	v_add_f32_e32 v7, v48, v7
	s_nop 1
	v_add_f32_dpp v7, v7, v7 quad_perm:[1,0,3,2] row_mask:0xf bank_mask:0xf
	v_pk_mul_f32 v[26:27], v[26:27], v[76:77]
	s_waitcnt lgkmcnt(0)
	s_nop 1
	v_add_f32_dpp v7, v7, v7 quad_perm:[2,3,0,1] row_mask:0xf bank_mask:0xf
	s_waitcnt lgkmcnt(0)
	s_nop 1
	v_add_f32_dpp v7, v7, v7 row_half_mirror row_mask:0xf bank_mask:0xf
	s_waitcnt lgkmcnt(0)
	v_fmamk_f32 v7, v7, 0x3c000000, v227
	v_cmp_gt_f32_e32 vcc, s24, v7
	v_mul_f32_e32 v8, 0x4b800000, v7
	s_nop 0
	v_cndmask_b32_e32 v7, v7, v8, vcc
	v_rsq_f32_e32 v7, v7
	s_nop 0
	v_mul_f32_e32 v8, 0x45800000, v7
	v_cndmask_b32_e32 v8, v7, v8, vcc
	v_mul_f32_e32 v7, 0xbfb8aa3b, v10
	v_exp_f32_e32 v7, v7
	v_pk_mul_f32 v[12:13], v[8:9], v[12:13] op_sel_hi:[0,1]
	v_pk_mul_f32 v[18:19], v[8:9], v[74:75] op_sel_hi:[0,1]
	s_waitcnt vmcnt(3)
	v_pk_mul_f32 v[12:13], v[32:33], v[12:13]
	v_add_f32_e32 v7, 1.0, v7
	v_rcp_f32_e32 v32, v7
	s_waitcnt vmcnt(0)
	v_pk_mul_f32 v[18:19], v[44:45], v[18:19]
	v_pk_mul_f32 v[20:21], v[8:9], v[68:69] op_sel_hi:[0,1]
	v_pk_mul_f32 v[18:19], v[26:27], v[18:19]
	v_pk_mul_f32 v[22:23], v[8:9], v[66:67] op_sel_hi:[0,1]
	v_pk_mul_f32 v[24:25], v[8:9], v[60:61] op_sel_hi:[0,1]
	v_pk_mul_f32 v[26:27], v[8:9], v[58:59] op_sel_hi:[0,1]
	v_pk_mul_f32 v[20:21], v[46:47], v[20:21]
	v_pk_mul_f32 v[22:23], v[40:41], v[22:23]
	v_pk_mul_f32 v[24:25], v[42:43], v[24:25]
	v_pk_mul_f32 v[26:27], v[36:37], v[26:27]
	v_mov_b32_e32 v33, v8
	v_pk_mul_f32 v[20:21], v[72:73], v[20:21]
	v_pk_mul_f32 v[22:23], v[28:29], v[22:23]
	v_pk_mul_f32 v[24:25], v[64:65], v[24:25]
	v_pk_mul_f32 v[26:27], v[30:31], v[26:27]
	v_pk_mul_f32 v[28:29], v[8:9], v[52:53] op_sel_hi:[0,1]
	v_mul_f32_e32 v30, v8, v9
	v_pk_mul_f32 v[8:9], v[32:33], v[10:11]
	v_pk_mul_f32 v[12:13], v[50:51], v[12:13]
	v_mov_b32_e32 v31, v9
	v_mov_b32_e32 v7, v8
	v_cvt_pk_bf16_f32 v8, v18, v19
	v_cvt_pk_bf16_f32 v9, v20, v21
	v_cvt_pk_bf16_f32 v10, v22, v23
	v_cvt_pk_bf16_f32 v11, v24, v25
	v_pk_mul_f32 v[28:29], v[38:39], v[28:29]
	global_store_dwordx4 v[4:5], v[8:11], off
	v_pk_mul_f32 v[28:29], v[56:57], v[28:29]
	s_nop 0
	v_cvt_pk_bf16_f32 v10, v12, v13
	v_pk_mul_f32 v[12:13], v[34:35], v[30:31]
	v_cvt_pk_bf16_f32 v8, v26, v27
	v_pk_mul_f32 v[6:7], v[6:7], v[12:13]
	v_cvt_pk_bf16_f32 v9, v28, v29
	v_cvt_pk_bf16_f32 v11, v6, v7
	global_store_dwordx4 v[4:5], v[8:11], off offset:16
	s_cbranch_scc1 .LBB0_131

; __device__ __forceinline__ void unpack8(const u32x4 w, float* f) { f[0] = bflo(w.x); f[1] = bfhi(w.x); f[2] = bflo(w.y); f[3] = bfhi(w.y); f[4] = bflo(w.z); f[5] = bfhi(w.z); f[6] = bflo(w.w); f[7] = bfhi(w.w); }
; __device__ __forceinline__ float siluf_(float x) { return x * sigmoidf_(x); }
; #define PREP_LOAD(p) do { _Pragma("unroll") for (int j = 0; j < 4; ++j) { const int rowi = (s - 3 + j >= 0) ? tg - 3 + j : tg; const bf16_t* row = QKV + (size_t)rowi * 3072 + (p) * 1024 + h * 128 + 16 * sub; \
;                 xr[(p) & 1][j][0] = *(const u32x4*)row; xr[(p) & 1][j][1] = *(const u32x4*)(row + 8); } } while (0)
; __device__ __forceinline__ void gdn_prep(KA a, int layer, unsigned char* lds, const int tid_, const int bid_) {
;     ...
;         float qkv[3][16];
; #pragma unroll
;         for (int p = 0; p < 3; ++p) {
; #pragma unroll
;             for (int e = 0; e < 16; ++e) qkv[p][e] = 0.f;
; #pragma unroll
;             for (int j = 0; j < 4; ++j) {
;                 const float vm = (s - 3 + j >= 0) ? 1.0f : 0.0f;
;                 float x[16]; unpack8(xr[p & 1][j][0], x); unpack8(xr[p & 1][j][1], x + 8);
;                 const f32x4* wp = (const f32x4*)(cwl + (p * 4 + j) * 128 + 16 * sub);
; #pragma unroll
;                 for (int q = 0; q < 4; ++q) { const f32x4 w4 = wp[q] * vm; qkv[p][4 * q] += w4.x * x[4 * q]; qkv[p][4 * q + 1] += w4.y * x[4 * q + 1]; qkv[p][4 * q + 2] += w4.z * x[4 * q + 2]; qkv[p][4 * q + 3] += w4.w * x[4 * q + 3]; }
;             }
;             if (p == 0) { asm volatile("" ::: "memory"); PREP_LOAD(2); }
; #pragma unroll
;             for (int e = 0; e < 16; ++e) qkv[p][e] = siluf_(qkv[p][e]);
.LBB0_219:
	s_or_b64 exec, exec, s[92:93]
	v_add_u32_e32 v5, 0, v150
	v_add_u32_e32 v181, 0x1f600, v5
	ds_read_b128 v[8:11], v181
	v_cmp_lt_u32_e64 s[90:91], 2, v4
	ds_read_b128 v[12:15], v181 offset:16
	ds_read_b128 v[82:85], v181 offset:32
	ds_read_b128 v[86:89], v181 offset:48
	v_cndmask_b32_e64 v110, 0, 1.0, s[90:91]
	v_cmp_lt_u32_e64 s[90:91], 1, v4
	s_waitcnt lgkmcnt(0)
	v_pk_mul_f32 v[130:131], v[110:111], v[8:9] op_sel_hi:[0,1]
	v_pk_mul_f32 v[138:139], v[110:111], v[10:11] op_sel_hi:[0,1]
	ds_read_b128 v[8:11], v181 offset:512
	v_cndmask_b32_e64 v112, 0, 1.0, s[90:91]
	v_pk_mul_f32 v[184:185], v[110:111], v[12:13] op_sel_hi:[0,1]
	v_pk_mul_f32 v[204:205], v[110:111], v[14:15] op_sel_hi:[0,1]
	v_pk_mul_f32 v[122:123], v[110:111], v[82:83] op_sel_hi:[0,1]
	v_pk_mul_f32 v[126:127], v[110:111], v[84:85] op_sel_hi:[0,1]
	ds_read_b128 v[12:15], v181 offset:528
	s_waitcnt lgkmcnt(0)
	v_pk_mul_f32 v[134:135], v[112:113], v[8:9] op_sel_hi:[0,1]
	ds_read_b128 v[82:85], v181 offset:544
	v_pk_mul_f32 v[142:143], v[112:113], v[10:11] op_sel_hi:[0,1]
	ds_read_b128 v[8:11], v181 offset:560
	v_pk_mul_f32 v[208:209], v[112:113], v[12:13] op_sel_hi:[0,1]
	v_cmp_eq_u32_e64 s[90:91], 0, v4
	v_pk_mul_f32 v[210:211], v[112:113], v[14:15] op_sel_hi:[0,1]
	s_waitcnt lgkmcnt(0)
	v_pk_mul_f32 v[124:125], v[112:113], v[82:83] op_sel_hi:[0,1]
	v_pk_mul_f32 v[212:213], v[112:113], v[10:11] op_sel_hi:[0,1]
	ds_read_b128 v[10:13], v181 offset:1024
	ds_read_b128 v[14:17], v181 offset:1040
	v_cndmask_b32_e64 v114, 1.0, 0, s[90:91]
	v_pk_mul_f32 v[132:133], v[112:113], v[84:85] op_sel_hi:[0,1]
	v_pk_mul_f32 v[214:215], v[112:113], v[8:9] op_sel_hi:[0,1]
	s_waitcnt lgkmcnt(0)
	v_pk_mul_f32 v[140:141], v[114:115], v[10:11] op_sel_hi:[0,1]
	ds_read_b128 v[8:11], v181 offset:1056
	ds_read_b128 v[82:85], v181 offset:1072
	s_lshl_b32 s19, s31, 7
	s_lshl_b32 s88, s19, 1
	v_pk_mul_f32 v[182:183], v[110:111], v[88:89] op_sel_hi:[0,1]
	v_pk_mul_f32 v[206:207], v[110:111], v[86:87] op_sel_hi:[0,1]
	s_waitcnt lgkmcnt(0)
	v_pk_mul_f32 v[222:223], v[114:115], v[84:85] op_sel_hi:[0,1]
	v_pk_mul_f32 v[224:225], v[114:115], v[82:83] op_sel_hi:[0,1]
	ds_read_b128 v[86:89], v181 offset:1536
	ds_read_b128 v[200:203], v181 offset:1552
	ds_read_b128 v[82:85], v181 offset:1568
	ds_read_b128 v[118:121], v181 offset:1584
	v_lshl_add_u64 v[116:117], v[116:117], 0, s[88:89]
	v_lshl_add_u64 v[236:237], v[116:117], 0, v[0:1]
	s_waitcnt vmcnt(0)
	v_and_b32_e32 v117, 0xffff0000, v56
	v_lshlrev_b32_e32 v116, 16, v56
	v_pk_fma_f32 v[116:117], v[206:207], v[116:117], 0 op_sel_hi:[1,1,0]
	v_and_b32_e32 v207, 0xffff0000, v60
	v_lshlrev_b32_e32 v206, 16, v60
	v_pk_fma_f32 v[116:117], v[214:215], v[206:207], v[116:117]
	v_and_b32_e32 v207, 0xffff0000, v64
	v_lshlrev_b32_e32 v206, 16, v64
	v_pk_fma_f32 v[116:117], v[224:225], v[206:207], v[116:117]
	v_and_b32_e32 v207, 0xffff0000, v52
	v_lshlrev_b32_e32 v206, 16, v52
	s_waitcnt lgkmcnt(0)
	v_pk_fma_f32 v[118:119], v[118:119], v[206:207], v[116:117]
	v_and_b32_e32 v215, 0xffff0000, v57
	v_mul_f32_e32 v56, 0xbfb8aa3b, v118
	v_exp_f32_e32 v56, v56
	v_mul_f32_e32 v52, 0xbfb8aa3b, v119
	v_exp_f32_e32 v52, v52
	v_lshlrev_b32_e32 v214, 16, v57
	v_add_f32_e32 v64, 1.0, v56
	v_pk_fma_f32 v[56:57], v[182:183], v[214:215], 0 op_sel_hi:[1,1,0]
	v_and_b32_e32 v183, 0xffff0000, v61
	v_lshlrev_b32_e32 v182, 16, v61
	v_pk_fma_f32 v[56:57], v[212:213], v[182:183], v[56:57]
	v_and_b32_e32 v61, 0xffff0000, v65
	v_lshlrev_b32_e32 v60, 16, v65
	v_add_f32_e32 v52, 1.0, v52
	v_pk_fma_f32 v[56:57], v[222:223], v[60:61], v[56:57]
	v_and_b32_e32 v61, 0xffff0000, v53
	v_lshlrev_b32_e32 v60, 16, v53
	v_rcp_f32_e32 v207, v52
	v_pk_fma_f32 v[52:53], v[120:121], v[60:61], v[56:57]
	v_lshl_add_u64 v[2:3], v[2:3], 0, s[88:89]
	v_mul_f32_e32 v56, 0xbfb8aa3b, v53
	v_exp_f32_e32 v56, v56
	v_mul_f32_e32 v57, 0xbfb8aa3b, v52
	v_exp_f32_e32 v57, v57
	v_lshl_add_u64 v[2:3], v[2:3], 0, v[0:1]
	v_add_f32_e32 v56, 1.0, v56
	s_mov_b64 s[20:21], 0x1000
	v_rcp_f32_e32 v61, v56
	v_add_f32_e32 v56, 1.0, v57
	v_lshl_add_u64 v[4:5], v[2:3], 0, s[20:21]
	v_add_co_u32_e64 v2, s[90:91], s23, v2
	v_lshl_add_u64 v[6:7], v[6:7], 0, s[88:89]
	v_rcp_f32_e32 v60, v56
	v_addc_co_u32_e64 v3, s[90:91], 0, v3, s[90:91]
	v_lshl_add_u64 v[6:7], v[6:7], 0, v[0:1]
	v_pk_mul_f32 v[128:129], v[114:115], v[8:9] op_sel_hi:[0,1]
	v_lshl_add_u64 v[8:9], v[6:7], 0, s[20:21]
	v_add_co_u32_e64 v6, s[90:91], s23, v6
	v_rcp_f32_e32 v206, v64
	s_nop 0
	v_addc_co_u32_e64 v7, s[90:91], 0, v7, s[90:91]
	v_add_co_u32_e64 v64, s[90:91], s23, v236
	v_pk_mul_f32 v[60:61], v[52:53], v[60:61]
	v_and_b32_e32 v53, 64, v233
	v_addc_co_u32_e64 v65, s[90:91], 0, v237, s[90:91]
	v_xor_b32_e32 v52, 1, v233
	v_add_u32_e32 v182, 64, v53
	v_cmp_lt_i32_e64 s[90:91], v52, v182
	v_and_b32_e32 v53, 0xffff0000, v73
	v_pk_mul_f32 v[220:221], v[114:115], v[16:17] op_sel_hi:[0,1]
	v_cndmask_b32_e64 v183, v233, v52, s[90:91]
	v_lshlrev_b32_e32 v52, 16, v73
	v_pk_fma_f32 v[52:53], v[204:205], v[52:53], 0 op_sel_hi:[1,1,0]
	v_lshlrev_b32_e32 v204, 16, v77
	v_and_b32_e32 v205, 0xffff0000, v77
	v_pk_fma_f32 v[52:53], v[210:211], v[204:205], v[52:53]
	v_lshlrev_b32_e32 v204, 16, v81
	v_and_b32_e32 v205, 0xffff0000, v81
	v_pk_fma_f32 v[52:53], v[220:221], v[204:205], v[52:53]
	v_lshlrev_b32_e32 v204, 16, v69
	v_and_b32_e32 v205, 0xffff0000, v69
	v_pk_fma_f32 v[52:53], v[202:203], v[204:205], v[52:53]
	v_lshlrev_b32_e32 v204, 16, v72
	v_mul_f32_e32 v69, 0xbfb8aa3b, v53
	v_exp_f32_e32 v69, v69
	v_mul_f32_e32 v73, 0xbfb8aa3b, v52
	v_exp_f32_e32 v73, v73
	v_and_b32_e32 v205, 0xffff0000, v72
	v_add_f32_e32 v69, 1.0, v69
	v_rcp_f32_e32 v203, v69
	v_add_f32_e32 v69, 1.0, v73
; __device__ __forceinline__ void unpack8(const u32x4 w, float* f) { f[0] = bflo(w.x); f[1] = bfhi(w.x); f[2] = bflo(w.y); f[3] = bfhi(w.y); f[4] = bflo(w.z); f[5] = bfhi(w.z); f[6] = bflo(w.w); f[7] = bfhi(w.w); }
; __device__ __forceinline__ float siluf_(float x) { return x * sigmoidf_(x); }
; #define PREP_LOAD(p) do { _Pragma("unroll") for (int j = 0; j < 4; ++j) { const int rowi = (s - 3 + j >= 0) ? tg - 3 + j : tg; const bf16_t* row = QKV + (size_t)rowi * 3072 + (p) * 1024 + h * 128 + 16 * sub; \
;                 xr[(p) & 1][j][0] = *(const u32x4*)row; xr[(p) & 1][j][1] = *(const u32x4*)(row + 8); } } while (0)
; __device__ __forceinline__ void gdn_prep(KA a, int layer, unsigned char* lds, const int tid_, const int bid_) {
;     ...
;         float qkv[3][16];
; #pragma unroll
;         for (int p = 0; p < 3; ++p) {
; #pragma unroll
;             for (int e = 0; e < 16; ++e) qkv[p][e] = 0.f;
; #pragma unroll
;             for (int j = 0; j < 4; ++j) {
;                 const float vm = (s - 3 + j >= 0) ? 1.0f : 0.0f;
;                 float x[16]; unpack8(xr[p & 1][j][0], x); unpack8(xr[p & 1][j][1], x + 8);
;                 const f32x4* wp = (const f32x4*)(cwl + (p * 4 + j) * 128 + 16 * sub);
; #pragma unroll
;                 for (int q = 0; q < 4; ++q) { const f32x4 w4 = wp[q] * vm; qkv[p][4 * q] += w4.x * x[4 * q]; qkv[p][4 * q + 1] += w4.y * x[4 * q + 1]; qkv[p][4 * q + 2] += w4.z * x[4 * q + 2]; qkv[p][4 * q + 3] += w4.w * x[4 * q + 3]; }
;             }
;             if (p == 0) { asm volatile("" ::: "memory"); PREP_LOAD(2); }
; #pragma unroll
;             for (int e = 0; e < 16; ++e) qkv[p][e] = siluf_(qkv[p][e]);
	v_pk_fma_f32 v[72:73], v[184:185], v[204:205], 0 op_sel_hi:[1,1,0]
	v_lshlrev_b32_e32 v184, 16, v76
	v_and_b32_e32 v185, 0xffff0000, v76
	v_pk_mul_f32 v[218:219], v[114:115], v[14:15] op_sel_hi:[0,1]
	v_pk_fma_f32 v[72:73], v[208:209], v[184:185], v[72:73]
	v_lshlrev_b32_e32 v76, 16, v80
	v_and_b32_e32 v77, 0xffff0000, v80
	v_pk_fma_f32 v[72:73], v[218:219], v[76:77], v[72:73]
	v_lshlrev_b32_e32 v76, 16, v68
	v_and_b32_e32 v77, 0xffff0000, v68
	v_pk_fma_f32 v[72:73], v[200:201], v[76:77], v[72:73]
	v_rcp_f32_e32 v202, v69
	v_mul_f32_e32 v68, 0xbfb8aa3b, v73
	v_exp_f32_e32 v76, v68
	v_mul_f32_e32 v68, 0xbfb8aa3b, v72
	v_exp_f32_e32 v77, v68
	v_pk_mul_f32 v[68:69], v[52:53], v[202:203]
	v_add_f32_e32 v52, 1.0, v76
	v_rcp_f32_e32 v53, v52
	v_add_f32_e32 v52, 1.0, v77
	v_lshlrev_b32_e32 v76, 16, v71
	v_and_b32_e32 v77, 0xffff0000, v71
	v_pk_fma_f32 v[76:77], v[138:139], v[76:77], 0 op_sel_hi:[1,1,0]
	v_lshlrev_b32_e32 v80, 16, v75
	v_and_b32_e32 v81, 0xffff0000, v75
	v_pk_mul_f32 v[216:217], v[114:115], v[12:13] op_sel_hi:[0,1]
	v_pk_fma_f32 v[76:77], v[142:143], v[80:81], v[76:77]
	v_lshlrev_b32_e32 v80, 16, v79
	v_and_b32_e32 v81, 0xffff0000, v79
	v_pk_fma_f32 v[76:77], v[216:217], v[80:81], v[76:77]
	v_lshlrev_b32_e32 v80, 16, v67
	v_and_b32_e32 v81, 0xffff0000, v67
	v_pk_fma_f32 v[76:77], v[88:89], v[80:81], v[76:77]
	v_rcp_f32_e32 v52, v52
	v_mul_f32_e32 v67, 0xbfb8aa3b, v77
	v_exp_f32_e32 v67, v67
	v_mul_f32_e32 v71, 0xbfb8aa3b, v76
	v_exp_f32_e32 v71, v71
	v_pk_mul_f32 v[72:73], v[72:73], v[52:53]
	v_add_f32_e32 v52, 1.0, v67
	v_lshlrev_b32_e32 v80, 16, v70
	v_and_b32_e32 v81, 0xffff0000, v70
	v_rcp_f32_e32 v53, v52
	v_add_f32_e32 v52, 1.0, v71
	v_pk_fma_f32 v[70:71], v[130:131], v[80:81], 0 op_sel_hi:[1,1,0]
	v_lshlrev_b32_e32 v80, 16, v74
	v_and_b32_e32 v81, 0xffff0000, v74
	v_pk_fma_f32 v[70:71], v[134:135], v[80:81], v[70:71]
	v_lshlrev_b32_e32 v74, 16, v78
	v_and_b32_e32 v75, 0xffff0000, v78
	v_pk_fma_f32 v[70:71], v[140:141], v[74:75], v[70:71]
	v_lshlrev_b32_e32 v74, 16, v66
	v_and_b32_e32 v75, 0xffff0000, v66
	v_pk_fma_f32 v[70:71], v[86:87], v[74:75], v[70:71]
	v_rcp_f32_e32 v52, v52
	v_mul_f32_e32 v66, 0xbfb8aa3b, v71
	v_exp_f32_e32 v74, v66
	v_mul_f32_e32 v66, 0xbfb8aa3b, v70
	v_exp_f32_e32 v75, v66
	v_pk_mul_f32 v[66:67], v[76:77], v[52:53]
	v_add_f32_e32 v52, 1.0, v74
	v_rcp_f32_e32 v53, v52
	v_add_f32_e32 v52, 1.0, v75
	v_lshlrev_b32_e32 v74, 16, v55
	v_and_b32_e32 v75, 0xffff0000, v55
	v_pk_fma_f32 v[74:75], v[126:127], v[74:75], 0 op_sel_hi:[1,1,0]
	v_lshlrev_b32_e32 v76, 16, v59
	v_and_b32_e32 v77, 0xffff0000, v59
	v_pk_mul_f32 v[136:137], v[114:115], v[10:11] op_sel_hi:[0,1]
	v_pk_fma_f32 v[74:75], v[132:133], v[76:77], v[74:75]
	v_lshlrev_b32_e32 v76, 16, v63
	v_and_b32_e32 v77, 0xffff0000, v63
	v_pk_fma_f32 v[74:75], v[136:137], v[76:77], v[74:75]
	v_lshlrev_b32_e32 v76, 16, v51
	v_and_b32_e32 v77, 0xffff0000, v51
	v_pk_fma_f32 v[74:75], v[84:85], v[76:77], v[74:75]
	v_lshlrev_b32_e32 v76, 16, v54
	v_mul_f32_e32 v55, 0xbfb8aa3b, v74
	v_exp_f32_e32 v55, v55
	v_and_b32_e32 v77, 0xffff0000, v54
	v_and_b32_e32 v59, 0xffff0000, v62
	v_mul_f32_e32 v51, 0xbfb8aa3b, v75
	v_add_f32_e32 v63, 1.0, v55
	v_pk_fma_f32 v[54:55], v[122:123], v[76:77], 0 op_sel_hi:[1,1,0]
	v_lshlrev_b32_e32 v76, 16, v58
	v_and_b32_e32 v77, 0xffff0000, v58
	v_pk_fma_f32 v[54:55], v[124:125], v[76:77], v[54:55]
	v_lshlrev_b32_e32 v58, 16, v62
	v_pk_fma_f32 v[54:55], v[128:129], v[58:59], v[54:55]
	v_lshlrev_b32_e32 v58, 16, v50
	v_and_b32_e32 v59, 0xffff0000, v50
	v_pk_fma_f32 v[76:77], v[82:83], v[58:59], v[54:55]
	v_exp_f32_e32 v51, v51
	v_mul_f32_e32 v50, 0xbfb8aa3b, v77
	v_exp_f32_e32 v54, v50
	v_mul_f32_e32 v50, 0xbfb8aa3b, v76
	v_exp_f32_e32 v55, v50
	v_add_f32_e32 v51, 1.0, v51
	v_add_f32_e32 v54, 1.0, v54
	v_rcp_f32_e32 v79, v54
	v_add_f32_e32 v54, 1.0, v55
	v_rcp_f32_e32 v52, v52
	v_rcp_f32_e32 v51, v51
	v_rcp_f32_e32 v50, v63
	v_rcp_f32_e32 v78, v54
	global_load_dwordx4 v[10:13], v[2:3], off
	s_nop 0
	global_load_dwordx4 v[2:5], v[4:5], off offset:16
	s_nop 0
	global_load_dwordx4 v[14:17], v[6:7], off
	s_nop 0
	global_load_dwordx4 v[6:9], v[8:9], off offset:16
	v_pk_mul_f32 v[58:59], v[70:71], v[52:53]
	v_pk_mul_f32 v[54:55], v[74:75], v[50:51]
	v_pk_mul_f32 v[76:77], v[76:77], v[78:79]
	ds_read_b128 v[50:53], v181 offset:2080
	ds_read_b128 v[78:81], v181 offset:2096
	ds_read_b128 v[122:125], v181 offset:2048
	ds_read_b128 v[126:129], v181 offset:2064
	ds_read_b128 v[82:85], v181 offset:2608
	v_pk_mul_f32 v[56:57], v[118:119], v[206:207]
	v_pk_mul_f32 v[70:71], v[76:77], v[76:77]
	s_waitcnt lgkmcnt(2)
	v_pk_mul_f32 v[218:219], v[110:111], v[122:123] op_sel_hi:[0,1]
	v_pk_mul_f32 v[142:143], v[110:111], v[80:81] op_sel_hi:[0,1]
	v_pk_mul_f32 v[184:185], v[110:111], v[78:79] op_sel_hi:[0,1]
	ds_read_b128 v[78:81], v181 offset:3120
	ds_read_b128 v[130:133], v181 offset:2592
	ds_read_b128 v[134:137], v181 offset:3104
	v_and_b32_e32 v123, 0xffff0000, v20
	v_lshlrev_b32_e32 v122, 16, v20
	s_waitcnt lgkmcnt(3)
	v_pk_mul_f32 v[200:201], v[112:113], v[84:85] op_sel_hi:[0,1]
	v_pk_mul_f32 v[202:203], v[112:113], v[82:83] op_sel_hi:[0,1]
	s_waitcnt lgkmcnt(2)
	v_pk_mul_f32 v[204:205], v[114:115], v[80:81] op_sel_hi:[0,1]
	v_pk_mul_f32 v[82:83], v[110:111], v[50:51] op_sel_hi:[0,1]
	v_pk_mul_f32 v[88:89], v[110:111], v[52:53] op_sel_hi:[0,1]
	s_waitcnt lgkmcnt(1)
	v_pk_mul_f32 v[80:81], v[112:113], v[130:131] op_sel_hi:[0,1]
	v_pk_mul_f32 v[86:87], v[112:113], v[132:133] op_sel_hi:[0,1]
	s_waitcnt lgkmcnt(0)
; __device__ __forceinline__ void unpack8(const u32x4 w, float* f) { f[0] = bflo(w.x); f[1] = bfhi(w.x); f[2] = bflo(w.y); f[3] = bfhi(w.y); f[4] = bflo(w.z); f[5] = bfhi(w.z); f[6] = bflo(w.w); f[7] = bfhi(w.w); }
; __device__ __forceinline__ float siluf_(float x) { return x * sigmoidf_(x); }
; #define PREP_LOAD(p) do { _Pragma("unroll") for (int j = 0; j < 4; ++j) { const int rowi = (s - 3 + j >= 0) ? tg - 3 + j : tg; const bf16_t* row = QKV + (size_t)rowi * 3072 + (p) * 1024 + h * 128 + 16 * sub; \
;                 xr[(p) & 1][j][0] = *(const u32x4*)row; xr[(p) & 1][j][1] = *(const u32x4*)(row + 8); } } while (0)
; __device__ __forceinline__ void gdn_prep(KA a, int layer, unsigned char* lds, const int tid_, const int bid_) {
;     ...
;         float qkv[3][16];
; #pragma unroll
;         for (int p = 0; p < 3; ++p) {
; #pragma unroll
;             for (int e = 0; e < 16; ++e) qkv[p][e] = 0.f;
; #pragma unroll
;             for (int j = 0; j < 4; ++j) {
;                 const float vm = (s - 3 + j >= 0) ? 1.0f : 0.0f;
;                 float x[16]; unpack8(xr[p & 1][j][0], x); unpack8(xr[p & 1][j][1], x + 8);
;                 const f32x4* wp = (const f32x4*)(cwl + (p * 4 + j) * 128 + 16 * sub);
; #pragma unroll
;                 for (int q = 0; q < 4; ++q) { const f32x4 w4 = wp[q] * vm; qkv[p][4 * q] += w4.x * x[4 * q]; qkv[p][4 * q + 1] += w4.y * x[4 * q + 1]; qkv[p][4 * q + 2] += w4.z * x[4 * q + 2]; qkv[p][4 * q + 3] += w4.w * x[4 * q + 3]; }
;             }
;             if (p == 0) { asm volatile("" ::: "memory"); PREP_LOAD(2); }
; #pragma unroll
;             for (int e = 0; e < 16; ++e) qkv[p][e] = siluf_(qkv[p][e]);
	v_pk_mul_f32 v[74:75], v[114:115], v[134:135] op_sel_hi:[0,1]
	v_pk_mul_f32 v[84:85], v[114:115], v[136:137] op_sel_hi:[0,1]
	ds_read_b128 v[130:133], v181 offset:3632
	ds_read_b128 v[50:53], v181 offset:3616
	ds_read_b128 v[134:137], v181 offset:2576
	v_pk_mul_f32 v[220:221], v[110:111], v[124:125] op_sel_hi:[0,1]
	v_pk_fma_f32 v[122:123], v[184:185], v[122:123], 0 op_sel_hi:[1,1,0]
	v_and_b32_e32 v125, 0xffff0000, v24
	v_lshlrev_b32_e32 v124, 16, v24
	v_pk_mul_f32 v[78:79], v[114:115], v[78:79] op_sel_hi:[0,1]
	v_pk_fma_f32 v[122:123], v[202:203], v[124:125], v[122:123]
	v_and_b32_e32 v125, 0xffff0000, v28
	v_lshlrev_b32_e32 v124, 16, v28
	v_pk_fma_f32 v[78:79], v[78:79], v[124:125], v[122:123]
	v_and_b32_e32 v123, 0xffff0000, v32
	v_lshlrev_b32_e32 v122, 16, v32
	s_waitcnt lgkmcnt(2)
	v_pk_fma_f32 v[78:79], v[130:131], v[122:123], v[78:79]
	v_pk_mul_f32 v[206:207], v[110:111], v[126:127] op_sel_hi:[0,1]
	v_mul_f32_e32 v20, 0xbfb8aa3b, v79
	v_pk_mul_f32 v[208:209], v[110:111], v[128:129] op_sel_hi:[0,1]
	ds_read_b128 v[126:129], v181 offset:3088
	ds_read_b128 v[138:141], v181 offset:2560
	s_waitcnt lgkmcnt(2)
	v_pk_mul_f32 v[210:211], v[112:113], v[134:135] op_sel_hi:[0,1]
	v_pk_mul_f32 v[212:213], v[112:113], v[136:137] op_sel_hi:[0,1]
	ds_read_b128 v[134:137], v181 offset:3072
	v_exp_f32_e32 v20, v20
	v_mul_f32_e32 v24, 0xbfb8aa3b, v78
	v_exp_f32_e32 v24, v24
	v_and_b32_e32 v123, 0xffff0000, v21
	v_add_f32_e32 v20, 1.0, v20
	v_lshlrev_b32_e32 v122, 16, v21
	s_waitcnt lgkmcnt(0)
	v_pk_mul_f32 v[130:131], v[114:115], v[136:137] op_sel_hi:[0,1]
	v_rcp_f32_e32 v137, v20
	v_pk_fma_f32 v[20:21], v[142:143], v[122:123], 0 op_sel_hi:[1,1,0]
	v_and_b32_e32 v123, 0xffff0000, v25
	v_lshlrev_b32_e32 v122, 16, v25
	v_add_f32_e32 v28, 1.0, v24
	v_pk_fma_f32 v[20:21], v[200:201], v[122:123], v[20:21]
	v_and_b32_e32 v25, 0xffff0000, v29
	v_lshlrev_b32_e32 v24, 16, v29
	v_pk_fma_f32 v[20:21], v[204:205], v[24:25], v[20:21]
	v_and_b32_e32 v25, 0xffff0000, v33
	v_lshlrev_b32_e32 v24, 16, v33
	v_pk_fma_f32 v[24:25], v[132:133], v[24:25], v[20:21]
	v_rcp_f32_e32 v136, v28
	v_mul_f32_e32 v20, 0xbfb8aa3b, v25
	v_exp_f32_e32 v20, v20
	v_mul_f32_e32 v21, 0xbfb8aa3b, v24
	v_exp_f32_e32 v21, v21
	v_pk_mul_f32 v[214:215], v[114:115], v[126:127] op_sel_hi:[0,1]
	v_add_f32_e32 v20, 1.0, v20
	v_rcp_f32_e32 v33, v20
	v_add_f32_e32 v20, 1.0, v21
	v_rcp_f32_e32 v32, v20
	v_pk_mul_f32 v[216:217], v[114:115], v[128:129] op_sel_hi:[0,1]
	ds_read_b128 v[122:125], v181 offset:3600
	ds_read_b128 v[126:129], v181 offset:3584
	v_pk_mul_f32 v[28:29], v[78:79], v[136:137]
	v_pk_mul_f32 v[78:79], v[24:25], v[32:33]
	v_lshlrev_b32_e32 v24, 16, v37
	v_and_b32_e32 v25, 0xffff0000, v37
	v_pk_fma_f32 v[24:25], v[208:209], v[24:25], 0 op_sel_hi:[1,1,0]
	v_lshlrev_b32_e32 v32, 16, v41
	v_and_b32_e32 v33, 0xffff0000, v41
	v_pk_fma_f32 v[24:25], v[212:213], v[32:33], v[24:25]
	v_lshlrev_b32_e32 v32, 16, v45
	v_and_b32_e32 v33, 0xffff0000, v45
	v_pk_fma_f32 v[24:25], v[216:217], v[32:33], v[24:25]
	v_lshlrev_b32_e32 v32, 16, v49
	v_and_b32_e32 v33, 0xffff0000, v49
	s_waitcnt lgkmcnt(1)
	v_pk_fma_f32 v[24:25], v[124:125], v[32:33], v[24:25]
	v_lshlrev_b32_e32 v132, 16, v36
	v_mul_f32_e32 v32, 0xbfb8aa3b, v25
	v_exp_f32_e32 v37, v32
	v_mul_f32_e32 v32, 0xbfb8aa3b, v24
	v_exp_f32_e32 v41, v32
	v_and_b32_e32 v133, 0xffff0000, v36
	v_add_f32_e32 v37, 1.0, v37
	v_rcp_f32_e32 v125, v37
	v_add_f32_e32 v37, 1.0, v41
	v_rcp_f32_e32 v124, v37
	v_pk_fma_f32 v[36:37], v[206:207], v[132:133], 0 op_sel_hi:[1,1,0]
	v_lshlrev_b32_e32 v132, 16, v40
	v_and_b32_e32 v133, 0xffff0000, v40
	v_pk_fma_f32 v[36:37], v[210:211], v[132:133], v[36:37]
	v_lshlrev_b32_e32 v40, 16, v44
	v_and_b32_e32 v41, 0xffff0000, v44
	v_pk_fma_f32 v[36:37], v[214:215], v[40:41], v[36:37]
	v_lshlrev_b32_e32 v40, 16, v48
	v_and_b32_e32 v41, 0xffff0000, v48
	v_pk_fma_f32 v[40:41], v[122:123], v[40:41], v[36:37]
	v_pk_mul_f32 v[140:141], v[112:113], v[140:141] op_sel_hi:[0,1]
	v_mul_f32_e32 v36, 0xbfb8aa3b, v41
	v_exp_f32_e32 v44, v36
	v_mul_f32_e32 v36, 0xbfb8aa3b, v40
	v_exp_f32_e32 v45, v36
	v_pk_mul_f32 v[36:37], v[24:25], v[124:125]
	v_add_f32_e32 v24, 1.0, v44
	v_rcp_f32_e32 v25, v24
	v_add_f32_e32 v24, 1.0, v45
	v_lshlrev_b32_e32 v44, 16, v35
	v_and_b32_e32 v45, 0xffff0000, v35
	v_pk_fma_f32 v[44:45], v[220:221], v[44:45], 0 op_sel_hi:[1,1,0]
	v_lshlrev_b32_e32 v48, 16, v39
	v_and_b32_e32 v49, 0xffff0000, v39
	v_pk_fma_f32 v[44:45], v[140:141], v[48:49], v[44:45]
	v_lshlrev_b32_e32 v48, 16, v43
	v_and_b32_e32 v49, 0xffff0000, v43
	v_pk_fma_f32 v[44:45], v[130:131], v[48:49], v[44:45]
	v_lshlrev_b32_e32 v48, 16, v47
	v_and_b32_e32 v49, 0xffff0000, v47
	s_waitcnt lgkmcnt(0)
; __device__ __forceinline__ float siluf_(float x) { return x * sigmoidf_(x); }
; __device__ __forceinline__ void gdn_prep(KA a, int layer, unsigned char* lds, const int tid_, const int bid_) {
;     ...
;             for (int e = 0; e < 16; ++e) qkv[p][e] = siluf_(qkv[p][e]);
;             if (p < 2) {
;                 float ss = 0.f;
; #pragma unroll
;                 for (int e = 0; e < 16; ++e) ss += qkv[p][e] * qkv[p][e];
;                 ss += __shfl_xor(ss, 1); ss += __shfl_xor(ss, 2); ss += __shfl_xor(ss, 4);
;                 const float sc = rsqrtf(ss + 1e-6f) * (p == 0 ? 0.08838834764831845f : 1.0f);
; #pragma unroll
;                 for (int e = 0; e < 16; ++e) qkv[p][e] *= sc;
	v_pk_fma_f32 v[44:45], v[128:129], v[48:49], v[44:45]
	v_rcp_f32_e32 v24, v24
	v_mul_f32_e32 v35, 0xbfb8aa3b, v45
	v_exp_f32_e32 v35, v35
	v_mul_f32_e32 v39, 0xbfb8aa3b, v44
	v_exp_f32_e32 v39, v39
	v_pk_mul_f32 v[48:49], v[40:41], v[24:25]
	v_lshlrev_b32_e32 v40, 16, v34
	v_and_b32_e32 v41, 0xffff0000, v34
	v_pk_mul_f32 v[138:139], v[112:113], v[138:139] op_sel_hi:[0,1]
	v_add_f32_e32 v24, 1.0, v35
	v_pk_fma_f32 v[34:35], v[218:219], v[40:41], 0 op_sel_hi:[1,1,0]
	v_lshlrev_b32_e32 v40, 16, v38
	v_and_b32_e32 v41, 0xffff0000, v38
	v_pk_mul_f32 v[134:135], v[114:115], v[134:135] op_sel_hi:[0,1]
	v_rcp_f32_e32 v25, v24
	v_add_f32_e32 v24, 1.0, v39
	v_pk_fma_f32 v[34:35], v[138:139], v[40:41], v[34:35]
	v_lshlrev_b32_e32 v38, 16, v42
	v_and_b32_e32 v39, 0xffff0000, v42
	v_pk_fma_f32 v[34:35], v[134:135], v[38:39], v[34:35]
	v_lshlrev_b32_e32 v38, 16, v46
	v_and_b32_e32 v39, 0xffff0000, v46
	v_pk_fma_f32 v[34:35], v[126:127], v[38:39], v[34:35]
	v_rcp_f32_e32 v24, v24
	v_mul_f32_e32 v38, 0xbfb8aa3b, v35
	v_exp_f32_e32 v38, v38
	v_mul_f32_e32 v39, 0xbfb8aa3b, v34
	v_exp_f32_e32 v39, v39
	v_pk_mul_f32 v[42:43], v[44:45], v[24:25]
	v_add_f32_e32 v24, 1.0, v38
	v_rcp_f32_e32 v25, v24
	v_add_f32_e32 v24, 1.0, v39
	v_lshlrev_b32_e32 v38, 16, v19
	v_and_b32_e32 v39, 0xffff0000, v19
	v_pk_fma_f32 v[38:39], v[88:89], v[38:39], 0 op_sel_hi:[1,1,0]
	v_lshlrev_b32_e32 v40, 16, v23
	v_and_b32_e32 v41, 0xffff0000, v23
	v_pk_fma_f32 v[38:39], v[86:87], v[40:41], v[38:39]
	v_lshlrev_b32_e32 v40, 16, v27
	v_and_b32_e32 v41, 0xffff0000, v27
	v_pk_fma_f32 v[38:39], v[84:85], v[40:41], v[38:39]
	v_lshlrev_b32_e32 v40, 16, v31
	v_and_b32_e32 v41, 0xffff0000, v31
	v_pk_fma_f32 v[38:39], v[52:53], v[40:41], v[38:39]
	v_lshlrev_b32_e32 v40, 16, v18
	v_mul_f32_e32 v23, 0xbfb8aa3b, v38
	v_exp_f32_e32 v23, v23
	v_and_b32_e32 v41, 0xffff0000, v18
	v_pk_fma_f32 v[40:41], v[82:83], v[40:41], 0 op_sel_hi:[1,1,0]
	v_lshlrev_b32_e32 v44, 16, v22
	v_and_b32_e32 v45, 0xffff0000, v22
	v_add_f32_e32 v31, 1.0, v23
	v_pk_fma_f32 v[22:23], v[80:81], v[44:45], v[40:41]
	v_lshlrev_b32_e32 v40, 16, v26
	v_and_b32_e32 v41, 0xffff0000, v26
	v_pk_fma_f32 v[22:23], v[74:75], v[40:41], v[22:23]
	v_lshlrev_b32_e32 v26, 16, v30
	v_and_b32_e32 v27, 0xffff0000, v30
	v_mul_f32_e32 v19, 0xbfb8aa3b, v39
	v_pk_fma_f32 v[22:23], v[50:51], v[26:27], v[22:23]
	v_exp_f32_e32 v19, v19
	v_rcp_f32_e32 v24, v24
	v_mul_f32_e32 v18, 0xbfb8aa3b, v23
	v_exp_f32_e32 v26, v18
	v_mul_f32_e32 v18, 0xbfb8aa3b, v22
	v_exp_f32_e32 v30, v18
	v_add_f32_e32 v19, 1.0, v19
	v_pk_mul_f32 v[34:35], v[34:35], v[24:25]
	v_rcp_f32_e32 v19, v19
	v_rcp_f32_e32 v18, v31
	v_add_f32_e32 v26, 1.0, v26
	v_mov_b32_e32 v74, v35
	v_mov_b32_e32 v75, v59
	v_rcp_f32_e32 v27, v26
	v_add_f32_e32 v26, 1.0, v30
	v_mov_b32_e32 v52, v34
	v_mov_b32_e32 v53, v58
	v_pk_mul_f32 v[74:75], v[74:75], v[74:75]
	v_rcp_f32_e32 v26, v26
	v_mov_b32_e32 v46, v42
	v_mov_b32_e32 v47, v66
	v_pk_fma_f32 v[52:53], v[52:53], v[52:53], v[74:75]
	v_mov_b32_e32 v50, v43
	v_mov_b32_e32 v51, v67
	v_pk_fma_f32 v[46:47], v[46:47], v[46:47], v[52:53]
	v_pk_mul_f32 v[44:45], v[38:39], v[18:19]
	v_mov_b32_e32 v38, v48
	v_mov_b32_e32 v39, v72
	v_pk_fma_f32 v[46:47], v[50:51], v[50:51], v[46:47]
	v_mov_b32_e32 v40, v49
	v_mov_b32_e32 v41, v73
	v_pk_fma_f32 v[38:39], v[38:39], v[38:39], v[46:47]
	v_pk_mul_f32 v[26:27], v[22:23], v[26:27]
	v_mov_b32_e32 v24, v36
	v_mov_b32_e32 v25, v68
	v_pk_fma_f32 v[38:39], v[40:41], v[40:41], v[38:39]
	v_pk_mul_f32 v[22:23], v[26:27], v[26:27]
	v_mov_b32_e32 v30, v37
	v_mov_b32_e32 v31, v69
	v_pk_fma_f32 v[24:25], v[24:25], v[24:25], v[38:39]
	v_pk_mul_f32 v[62:63], v[54:55], v[54:55]
	v_pk_fma_f32 v[24:25], v[30:31], v[30:31], v[24:25]
	v_mov_b32_e32 v30, v22
	v_mov_b32_e32 v31, v70
	v_pk_mul_f32 v[18:19], v[44:45], v[44:45]
	v_pk_add_f32 v[24:25], v[30:31], v[24:25]
	v_mov_b32_e32 v70, v23
	v_pk_add_f32 v[22:23], v[70:71], v[24:25]
	v_mov_b32_e32 v24, v18
	v_mov_b32_e32 v25, v62
	v_pk_mul_f32 v[120:121], v[56:57], v[56:57]
	v_pk_mul_f32 v[20:21], v[28:29], v[28:29]
	v_pk_add_f32 v[22:23], v[24:25], v[22:23]
	v_mov_b32_e32 v62, v19
	v_pk_add_f32 v[18:19], v[62:63], v[22:23]
	v_mov_b32_e32 v22, v20
	v_mov_b32_e32 v23, v120
	v_pk_mul_f32 v[118:119], v[60:61], v[60:61]
	v_pk_mul_f32 v[32:33], v[78:79], v[78:79]
	v_pk_add_f32 v[18:19], v[22:23], v[18:19]
	v_mov_b32_e32 v120, v21
	v_pk_add_f32 v[18:19], v[120:121], v[18:19]
	v_mov_b32_e32 v20, v32
	v_mov_b32_e32 v21, v118
	v_pk_add_f32 v[18:19], v[20:21], v[18:19]
	v_mov_b32_e32 v118, v33
	v_lshlrev_b32_e32 v183, 2, v183
	v_pk_add_f32 v[18:19], v[118:119], v[18:19]
	s_nop 1
	v_add_f32_dpp v18, v18, v18 quad_perm:[1,0,3,2] row_mask:0xf bank_mask:0xf
	v_add_f32_dpp v19, v19, v19 quad_perm:[1,0,3,2] row_mask:0xf bank_mask:0xf
	s_nop 0
	v_add_f32_dpp v18, v18, v18 quad_perm:[2,3,0,1] row_mask:0xf bank_mask:0xf
	v_add_f32_dpp v19, v19, v19 quad_perm:[2,3,0,1] row_mask:0xf bank_mask:0xf
	s_nop 0
	v_add_f32_dpp v22, v18, v18 row_half_mirror row_mask:0xf bank_mask:0xf
	v_add_f32_dpp v23, v19, v19 row_half_mirror row_mask:0xf bank_mask:0xf
	v_lshl_add_u64 v[38:39], v[108:109], 0, s[88:89]
	v_lshl_add_u64 v[38:39], v[38:39], 0, v[0:1]
	s_waitcnt lgkmcnt(0)
	v_lshl_add_u64 v[116:117], v[236:237], 0, s[20:21]
	v_lshl_add_u64 v[46:47], v[38:39], 0, s[20:21]
	s_waitcnt lgkmcnt(0)
	s_mov_b32 s20, 0x358637bd
	global_load_dwordx4 v[30:33], v[64:65], off
	global_load_dwordx4 v[18:21], v[116:117], off offset:16
	s_waitcnt vmcnt(5)
	v_lshlrev_b32_e32 v214, 16, v10
	v_and_b32_e32 v215, 0xffff0000, v10
	s_waitcnt lgkmcnt(0)
; __device__ __forceinline__ void unpack8(const u32x4 w, float* f) { f[0] = bflo(w.x); f[1] = bfhi(w.x); f[2] = bflo(w.y); f[3] = bfhi(w.y); f[4] = bflo(w.z); f[5] = bfhi(w.z); f[6] = bflo(w.w); f[7] = bfhi(w.w); }
; __device__ __forceinline__ float siluf_(float x) { return x * sigmoidf_(x); }
; #define PREP_LOAD(p) do { _Pragma("unroll") for (int j = 0; j < 4; ++j) { const int rowi = (s - 3 + j >= 0) ? tg - 3 + j : tg; const bf16_t* row = QKV + (size_t)rowi * 3072 + (p) * 1024 + h * 128 + 16 * sub; \
;                 xr[(p) & 1][j][0] = *(const u32x4*)row; xr[(p) & 1][j][1] = *(const u32x4*)(row + 8); } } while (0)
; __device__ __forceinline__ void gdn_prep(KA a, int layer, unsigned char* lds, const int tid_, const int bid_) {
;     ...
;         for (int p = 0; p < 3; ++p) {
; #pragma unroll
;             for (int e = 0; e < 16; ++e) qkv[p][e] = 0.f;
; #pragma unroll
;             for (int j = 0; j < 4; ++j) {
;                 const float vm = (s - 3 + j >= 0) ? 1.0f : 0.0f;
;                 float x[16]; unpack8(xr[p & 1][j][0], x); unpack8(xr[p & 1][j][1], x + 8);
;                 const f32x4* wp = (const f32x4*)(cwl + (p * 4 + j) * 128 + 16 * sub);
; #pragma unroll
;                 for (int q = 0; q < 4; ++q) { const f32x4 w4 = wp[q] * vm; qkv[p][4 * q] += w4.x * x[4 * q]; qkv[p][4 * q + 1] += w4.y * x[4 * q + 1]; qkv[p][4 * q + 2] += w4.z * x[4 * q + 2]; qkv[p][4 * q + 3] += w4.w * x[4 * q + 3]; }
;             }
;             if (p == 0) { asm volatile("" ::: "memory"); PREP_LOAD(2); }
; #pragma unroll
;             for (int e = 0; e < 16; ++e) qkv[p][e] = siluf_(qkv[p][e]);
;             if (p < 2) {
;                 float ss = 0.f;
; #pragma unroll
;                 for (int e = 0; e < 16; ++e) ss += qkv[p][e] * qkv[p][e];
;                 ss += __shfl_xor(ss, 1); ss += __shfl_xor(ss, 2); ss += __shfl_xor(ss, 4);
;                 const float sc = rsqrtf(ss + 1e-6f) * (p == 0 ? 0.08838834764831845f : 1.0f);
; #pragma unroll
;                 for (int e = 0; e < 16; ++e) qkv[p][e] *= sc;
;             }
;         }
	v_readlane_b32 s19, v255, 20
	v_pk_add_f32 v[50:51], v[22:23], s[20:21] op_sel_hi:[1,0]
	v_ashrrev_i32_e32 v107, 31, v106
	v_mul_f32_e32 v22, 0x4b800000, v51
	v_cmp_gt_f32_e64 s[90:91], s24, v51
	v_mov_b32_e32 v80, s19
	s_nop 0
	v_cndmask_b32_e64 v22, v51, v22, s[90:91]
	v_rsq_f32_e32 v51, v22
	v_add_co_u32_e64 v22, s[92:93], s23, v38
	s_nop 1
	v_addc_co_u32_e64 v23, s[92:93], 0, v39, s[92:93]
	global_load_dwordx4 v[38:41], v[22:23], off
	s_nop 0
	global_load_dwordx4 v[22:25], v[46:47], off offset:16
	v_mul_f32_e32 v46, 0x45800000, v51
	v_cndmask_b32_e64 v46, v51, v46, s[90:91]
	v_mul_f32_e32 v46, 0x3db504f3, v46
	v_pk_mul_f32 v[74:75], v[58:59], v[46:47] op_sel_hi:[1,0]
	v_pk_mul_f32 v[70:71], v[66:67], v[46:47] op_sel_hi:[1,0]
	v_pk_mul_f32 v[66:67], v[72:73], v[46:47] op_sel_hi:[1,0]
	v_pk_mul_f32 v[62:63], v[68:69], v[46:47] op_sel_hi:[1,0]
	v_pk_mul_f32 v[58:59], v[76:77], v[46:47] op_sel_hi:[1,0]
	v_mul_f32_e32 v47, 0x4b800000, v50
	v_cmp_gt_f32_e64 s[90:91], s24, v50
	s_nop 1
	v_cndmask_b32_e64 v47, v50, v47, s[90:91]
	v_rsq_f32_e32 v47, v47
	s_nop 0
	v_pk_mul_f32 v[68:69], v[54:55], v[46:47] op_sel_hi:[1,0]
	v_pk_mul_f32 v[64:65], v[56:57], v[46:47] op_sel_hi:[1,0]
	v_pk_mul_f32 v[60:61], v[60:61], v[46:47] op_sel_hi:[1,0]
	v_mul_f32_e32 v46, 0x45800000, v47
	v_cndmask_b32_e64 v72, v47, v46, s[90:91]
	v_pk_mul_f32 v[56:57], v[34:35], v[72:73] op_sel_hi:[1,0]
	v_pk_mul_f32 v[50:51], v[36:37], v[72:73] op_sel_hi:[1,0]
	ds_read_b128 v[34:37], v181 offset:4144
	v_pk_mul_f32 v[52:53], v[48:49], v[72:73] op_sel_hi:[1,0]
	v_pk_mul_f32 v[48:49], v[26:27], v[72:73] op_sel_hi:[1,0]
	v_pk_mul_f32 v[46:47], v[28:29], v[72:73] op_sel_hi:[1,0]
	ds_read_b128 v[26:29], v181 offset:4656
	ds_read_b128 v[116:119], v181 offset:4128
	v_pk_mul_f32 v[54:55], v[42:43], v[72:73] op_sel_hi:[1,0]
	v_pk_mul_f32 v[44:45], v[44:45], v[72:73] op_sel_hi:[1,0]
	v_pk_mul_f32 v[42:43], v[78:79], v[72:73] op_sel_hi:[1,0]
	s_waitcnt lgkmcnt(2)
	v_pk_mul_f32 v[72:73], v[110:111], v[36:37] op_sel_hi:[0,1]
	v_pk_mul_f32 v[82:83], v[110:111], v[34:35] op_sel_hi:[0,1]
	ds_read_b128 v[34:37], v181 offset:5168
	ds_read_b128 v[120:123], v181 offset:4640
	s_waitcnt lgkmcnt(3)
	v_pk_mul_f32 v[76:77], v[112:113], v[28:29] op_sel_hi:[0,1]
	v_pk_mul_f32 v[84:85], v[112:113], v[26:27] op_sel_hi:[0,1]
	ds_read_b128 v[26:29], v181 offset:5152
	s_waitcnt lgkmcnt(2)
	v_pk_mul_f32 v[78:79], v[114:115], v[36:37] op_sel_hi:[0,1]
	v_pk_mul_f32 v[86:87], v[114:115], v[34:35] op_sel_hi:[0,1]
	v_pk_mul_f32 v[124:125], v[110:111], v[116:117] op_sel_hi:[0,1]
	s_waitcnt lgkmcnt(1)
	v_pk_mul_f32 v[116:117], v[112:113], v[122:123] op_sel_hi:[0,1]
	v_pk_mul_f32 v[122:123], v[112:113], v[120:121] op_sel_hi:[0,1]
	s_waitcnt lgkmcnt(0)
	v_pk_mul_f32 v[108:109], v[114:115], v[28:29] op_sel_hi:[0,1]
	v_pk_mul_f32 v[120:121], v[114:115], v[26:27] op_sel_hi:[0,1]
	ds_read_b128 v[126:129], v181 offset:4112
	ds_read_b128 v[26:29], v181 offset:5680
	ds_read_b128 v[34:37], v181 offset:5664
	ds_read_b128 v[130:133], v181 offset:4624
	ds_read_b128 v[134:137], v181 offset:4096
	s_waitcnt lgkmcnt(4)
	v_pk_mul_f32 v[142:143], v[110:111], v[128:129] op_sel_hi:[0,1]
	v_pk_mul_f32 v[182:183], v[110:111], v[126:127] op_sel_hi:[0,1]
	ds_read_b128 v[126:129], v181 offset:5136
	ds_read_b128 v[138:141], v181 offset:4608
	s_waitcnt lgkmcnt(3)
	v_pk_mul_f32 v[184:185], v[112:113], v[132:133] op_sel_hi:[0,1]
	v_pk_mul_f32 v[200:201], v[112:113], v[130:131] op_sel_hi:[0,1]
	ds_read_b128 v[130:133], v181 offset:5120
	s_waitcnt lgkmcnt(2)
	v_pk_mul_f32 v[202:203], v[114:115], v[128:129] op_sel_hi:[0,1]
	v_pk_mul_f32 v[204:205], v[114:115], v[126:127] op_sel_hi:[0,1]
	v_pk_mul_f32 v[208:209], v[110:111], v[134:135] op_sel_hi:[0,1]
	s_waitcnt lgkmcnt(1)
	v_pk_mul_f32 v[210:211], v[112:113], v[138:139] op_sel_hi:[0,1]
	s_waitcnt lgkmcnt(0)
	v_pk_mul_f32 v[212:213], v[114:115], v[132:133] op_sel_hi:[0,1]
	ds_read_b128 v[126:129], v181 offset:5648
	ds_read_b128 v[132:135], v181 offset:5632
	v_pk_fma_f32 v[208:209], v[208:209], v[214:215], 0 op_sel_hi:[1,1,0]
	s_waitcnt vmcnt(5)
	v_lshlrev_b32_e32 v214, 16, v14
	v_and_b32_e32 v215, 0xffff0000, v14
	v_pk_mul_f32 v[130:131], v[114:115], v[130:131] op_sel_hi:[0,1]
	v_pk_fma_f32 v[208:209], v[210:211], v[214:215], v[208:209]
	s_waitcnt vmcnt(3)
	v_lshlrev_b32_e32 v210, 16, v30
	v_and_b32_e32 v211, 0xffff0000, v30
	v_pk_fma_f32 v[130:131], v[130:131], v[210:211], v[208:209]
	v_pk_mul_f32 v[206:207], v[110:111], v[136:137] op_sel_hi:[0,1]
	v_pk_mul_f32 v[140:141], v[112:113], v[140:141] op_sel_hi:[0,1]
	s_waitcnt lgkmcnt(0)
	s_barrier
; __device__ __forceinline__ u32x4 pack8(const float* f) { u32x4 w; w.x = cvt_pk_bf16(f[0], f[1]); w.y = cvt_pk_bf16(f[2], f[3]); w.z = cvt_pk_bf16(f[4], f[5]); w.w = cvt_pk_bf16(f[6], f[7]); return w; }
; __device__ __forceinline__ void gdn_prep(KA a, int layer, unsigned char* lds, const int tid_, const int bid_) {
;     ...
;         const float gci = gcs[tl], gl = gcs[63], bi = bts[tl];
;         const float eg = __expf(gci), ekd = __expf(gl - gci);
;         *(u32x4*)(Kb + tl * 272 + sub * 32) = pack8(qkv[1]); *(u32x4*)(Kb + tl * 272 + sub * 32 + 16) = pack8(qkv[1] + 8);
;         *(u32x4*)(Qb + tl * 272 + sub * 32) = pack8(qkv[0]); *(u32x4*)(Qb + tl * 272 + sub * 32 + 16) = pack8(qkv[0] + 8);
; #pragma unroll
;         for (int q = 0; q < 4; ++q) {
;             *(f32x4*)(RHS + tl * 260 + 16 * sub + 4 * q) = (f32x4){bi * qkv[2][4 * q], bi * qkv[2][4 * q + 1], bi * qkv[2][4 * q + 2], bi * qkv[2][4 * q + 3]};
;             const float bk = bi * eg;
;             *(f32x4*)(RHS + tl * 260 + 128 + 16 * sub + 4 * q) = (f32x4){bk * qkv[1][4 * q], bk * qkv[1][4 * q + 1], bk * qkv[1][4 * q + 2], bk * qkv[1][4 * q + 3]};
;         }
	ds_read_b32 v81, v151
	ds_read_b32 v89, v80
	ds_read_b32 v88, v152
	v_pk_mul_f32 v[118:119], v[110:111], v[118:119] op_sel_hi:[0,1]
	v_cvt_pk_bf16_f32 v136, v56, v57
	v_cvt_pk_bf16_f32 v137, v54, v55
	s_waitcnt lgkmcnt(2)
	v_mul_f32_e32 v80, 0x3fb8aa3b, v81
	v_exp_f32_e32 v80, v80
	s_waitcnt vmcnt(1)
	v_lshlrev_b32_e32 v208, 16, v38
	v_and_b32_e32 v209, 0xffff0000, v38
	v_pk_fma_f32 v[130:131], v[132:133], v[208:209], v[130:131]
	v_cvt_pk_bf16_f32 v138, v52, v53
	v_mul_f32_e32 v10, 0xbfb8aa3b, v131
	v_exp_f32_e32 v10, v10
	v_mul_f32_e32 v14, 0xbfb8aa3b, v130
	v_exp_f32_e32 v14, v14
	v_cvt_pk_bf16_f32 v139, v50, v51
	v_add_f32_e32 v10, 1.0, v10
	v_rcp_f32_e32 v133, v10
	v_lshlrev_b32_e32 v10, 16, v11
	v_and_b32_e32 v11, 0xffff0000, v11
	v_add_f32_e32 v30, 1.0, v14
	v_pk_fma_f32 v[10:11], v[206:207], v[10:11], 0 op_sel_hi:[1,1,0]
	v_lshlrev_b32_e32 v14, 16, v15
	v_and_b32_e32 v15, 0xffff0000, v15
	v_pk_fma_f32 v[10:11], v[140:141], v[14:15], v[10:11]
	v_lshlrev_b32_e32 v14, 16, v31
	v_and_b32_e32 v15, 0xffff0000, v31
	v_pk_fma_f32 v[10:11], v[212:213], v[14:15], v[10:11]
	v_lshlrev_b32_e32 v14, 16, v39
	v_and_b32_e32 v15, 0xffff0000, v39
	v_pk_fma_f32 v[14:15], v[134:135], v[14:15], v[10:11]
	v_rcp_f32_e32 v132, v30
	v_mul_f32_e32 v10, 0xbfb8aa3b, v15
	v_exp_f32_e32 v10, v10
	v_mul_f32_e32 v11, 0xbfb8aa3b, v14
	v_exp_f32_e32 v11, v11
	v_pk_mul_f32 v[38:39], v[130:131], v[132:133]
	v_add_f32_e32 v10, 1.0, v10
	v_rcp_f32_e32 v31, v10
	v_add_f32_e32 v10, 1.0, v11
	v_rcp_f32_e32 v30, v10
	s_waitcnt lgkmcnt(0)
	v_mul_f32_e32 v10, v88, v80
	v_pk_mul_f32 v[130:131], v[88:89], v[38:39] op_sel_hi:[0,1]
	v_add_u32_e32 v110, v98, v94
	v_pk_mul_f32 v[14:15], v[14:15], v[30:31]
	v_lshlrev_b32_e32 v30, 16, v16
	v_pk_mul_f32 v[132:133], v[88:89], v[14:15] op_sel_hi:[0,1]
	v_lshlrev_b32_e32 v14, 16, v12
	v_and_b32_e32 v15, 0xffff0000, v12
	v_pk_fma_f32 v[14:15], v[182:183], v[14:15], 0 op_sel_hi:[1,1,0]
	v_and_b32_e32 v31, 0xffff0000, v16
	v_pk_fma_f32 v[14:15], v[200:201], v[30:31], v[14:15]
	v_lshlrev_b32_e32 v30, 16, v32
	v_and_b32_e32 v31, 0xffff0000, v32
	v_pk_fma_f32 v[14:15], v[204:205], v[30:31], v[14:15]
	v_lshlrev_b32_e32 v30, 16, v40
	v_and_b32_e32 v31, 0xffff0000, v40
	v_pk_fma_f32 v[30:31], v[126:127], v[30:31], v[14:15]
	v_lshlrev_b32_e32 v16, 16, v17
	v_mul_f32_e32 v11, 0xbfb8aa3b, v31
	v_exp_f32_e32 v11, v11
	v_mul_f32_e32 v12, 0xbfb8aa3b, v30
	v_exp_f32_e32 v12, v12
	v_and_b32_e32 v17, 0xffff0000, v17
	v_pk_mul_f32 v[14:15], v[10:11], v[54:55] op_sel_hi:[0,1]
	v_add_f32_e32 v11, 1.0, v11
	v_rcp_f32_e32 v39, v11
	v_add_f32_e32 v11, 1.0, v12
	v_lshlrev_b32_e32 v12, 16, v13
	v_and_b32_e32 v13, 0xffff0000, v13
	v_pk_fma_f32 v[12:13], v[142:143], v[12:13], 0 op_sel_hi:[1,1,0]
	v_rcp_f32_e32 v38, v11
	v_pk_fma_f32 v[12:13], v[184:185], v[16:17], v[12:13]
	v_lshlrev_b32_e32 v16, 16, v33
	v_and_b32_e32 v17, 0xffff0000, v33
	v_pk_fma_f32 v[12:13], v[202:203], v[16:17], v[12:13]
	v_lshlrev_b32_e32 v16, 16, v41
	v_and_b32_e32 v17, 0xffff0000, v41
	v_pk_fma_f32 v[16:17], v[128:129], v[16:17], v[12:13]
	ds_write_b128 v110, v[136:139]
	v_mul_f32_e32 v12, 0xbfb8aa3b, v17
	v_exp_f32_e32 v12, v12
	v_mul_f32_e32 v13, 0xbfb8aa3b, v16
	v_exp_f32_e32 v13, v13
	v_cvt_pk_bf16_f32 v136, v48, v49
	v_add_f32_e32 v11, 1.0, v12
	v_rcp_f32_e32 v33, v11
	v_add_f32_e32 v11, 1.0, v13
	v_rcp_f32_e32 v32, v11
	v_cvt_pk_bf16_f32 v137, v44, v45
	v_cvt_pk_bf16_f32 v138, v46, v47
	v_cvt_pk_bf16_f32 v139, v42, v43
	ds_write_b128 v110, v[136:139] offset:16
	v_cvt_pk_bf16_f32 v136, v74, v75
	v_cvt_pk_bf16_f32 v137, v70, v71
	v_cvt_pk_bf16_f32 v138, v66, v67
	v_cvt_pk_bf16_f32 v139, v62, v63
	v_pk_mul_f32 v[12:13], v[10:11], v[56:57] op_sel_hi:[0,1]
	ds_write_b128 v110, v[136:139] offset:17408
	ds_write_b128 v153, v[12:15] offset:52736
	v_pk_mul_f32 v[12:13], v[30:31], v[38:39]
	v_pk_mul_f32 v[14:15], v[16:17], v[32:33]
	v_cvt_pk_bf16_f32 v136, v58, v59
	v_cvt_pk_bf16_f32 v137, v68, v69
	v_cvt_pk_bf16_f32 v138, v64, v65
	v_cvt_pk_bf16_f32 v139, v60, v61
	v_pk_mul_f32 v[14:15], v[14:15], v[88:89] op_sel_hi:[1,0]
	v_pk_mul_f32 v[12:13], v[12:13], v[88:89] op_sel_hi:[1,0]
	ds_write_b128 v110, v[136:139] offset:17424
	ds_write_b128 v153, v[12:15] offset:52240
	v_lshlrev_b32_e32 v12, 16, v2
	v_and_b32_e32 v13, 0xffff0000, v2
	v_pk_fma_f32 v[12:13], v[124:125], v[12:13], 0 op_sel_hi:[1,1,0]
	v_lshlrev_b32_e32 v14, 16, v6
	v_and_b32_e32 v15, 0xffff0000, v6
	v_pk_fma_f32 v[12:13], v[122:123], v[14:15], v[12:13]
	v_lshlrev_b32_e32 v14, 16, v18
	v_and_b32_e32 v15, 0xffff0000, v18
	v_pk_fma_f32 v[12:13], v[120:121], v[14:15], v[12:13]
	s_waitcnt vmcnt(0)
; __device__ __forceinline__ u32x4 pack8(const float* f) { u32x4 w; w.x = cvt_pk_bf16(f[0], f[1]); w.y = cvt_pk_bf16(f[2], f[3]); w.z = cvt_pk_bf16(f[4], f[5]); w.w = cvt_pk_bf16(f[6], f[7]); return w; }
; __device__ __forceinline__ void gdn_prep(KA a, int layer, unsigned char* lds, const int tid_, const int bid_) {
;     ...
; #pragma unroll
;         for (int q = 0; q < 4; ++q) {
;             *(f32x4*)(RHS + tl * 260 + 16 * sub + 4 * q) = (f32x4){bi * qkv[2][4 * q], bi * qkv[2][4 * q + 1], bi * qkv[2][4 * q + 2], bi * qkv[2][4 * q + 3]};
;             const float bk = bi * eg;
;             *(f32x4*)(RHS + tl * 260 + 128 + 16 * sub + 4 * q) = (f32x4){bk * qkv[1][4 * q], bk * qkv[1][4 * q + 1], bk * qkv[1][4 * q + 2], bk * qkv[1][4 * q + 3]};
;         }
;         {
;             float qd[16];
; #pragma unroll
;             for (int e = 0; e < 16; ++e) { qd[e] = qkv[0][e] * eg; qkv[1][e] *= ekd; }
;             bf16_t* dst = (bf16_t*)(ws + WS_QD) + (size_t)tg * 1024 + h * 128 + 16 * sub;
;             *(u32x4*)dst = pack8(qd); *(u32x4*)(dst + 8) = pack8(qd + 8);
;         }
	v_lshlrev_b32_e32 v14, 16, v22
	v_and_b32_e32 v15, 0xffff0000, v22
	v_pk_fma_f32 v[16:17], v[34:35], v[14:15], v[12:13]
	v_pk_mul_f32 v[14:15], v[10:11], v[50:51] op_sel_hi:[0,1]
	v_mul_f32_e32 v2, 0xbfb8aa3b, v17
	v_exp_f32_e32 v2, v2
	v_mul_f32_e32 v6, 0xbfb8aa3b, v16
	v_exp_f32_e32 v6, v6
	ds_write_b128 v153, v[130:133] offset:52224
	v_add_f32_e32 v2, 1.0, v2
	v_rcp_f32_e32 v31, v2
	v_lshlrev_b32_e32 v2, 16, v3
	v_and_b32_e32 v3, 0xffff0000, v3
	v_add_f32_e32 v11, 1.0, v6
	v_pk_fma_f32 v[2:3], v[118:119], v[2:3], 0 op_sel_hi:[1,1,0]
	v_lshlrev_b32_e32 v6, 16, v7
	v_and_b32_e32 v7, 0xffff0000, v7
	v_pk_fma_f32 v[2:3], v[116:117], v[6:7], v[2:3]
	v_lshlrev_b32_e32 v6, 16, v19
	v_and_b32_e32 v7, 0xffff0000, v19
	v_pk_fma_f32 v[2:3], v[108:109], v[6:7], v[2:3]
	v_lshlrev_b32_e32 v6, 16, v23
	v_and_b32_e32 v7, 0xffff0000, v23
	v_pk_fma_f32 v[2:3], v[36:37], v[6:7], v[2:3]
	v_rcp_f32_e32 v30, v11
	v_mul_f32_e32 v6, 0xbfb8aa3b, v3
	v_exp_f32_e32 v6, v6
	v_mul_f32_e32 v7, 0xbfb8aa3b, v2
	v_exp_f32_e32 v12, v7
	v_lshlrev_b64 v[18:19], 11, v[106:107]
	v_add_f32_e32 v6, 1.0, v6
	v_rcp_f32_e32 v7, v6
	v_add_f32_e32 v6, 1.0, v12
	v_rcp_f32_e32 v6, v6
	v_pk_mul_f32 v[12:13], v[10:11], v[52:53] op_sel_hi:[0,1]
	ds_write_b128 v153, v[12:15] offset:52752
	v_pk_mul_f32 v[12:13], v[16:17], v[30:31]
	v_pk_mul_f32 v[2:3], v[2:3], v[6:7]
	v_lshlrev_b32_e32 v6, 16, v8
	v_pk_mul_f32 v[14:15], v[2:3], v[88:89] op_sel_hi:[1,0]
	v_lshlrev_b32_e32 v2, 16, v4
	v_and_b32_e32 v3, 0xffff0000, v4
	v_pk_fma_f32 v[2:3], v[82:83], v[2:3], 0 op_sel_hi:[1,1,0]
	v_and_b32_e32 v7, 0xffff0000, v8
	v_pk_fma_f32 v[2:3], v[84:85], v[6:7], v[2:3]
	v_lshlrev_b32_e32 v6, 16, v20
	v_and_b32_e32 v7, 0xffff0000, v20
	v_pk_fma_f32 v[2:3], v[86:87], v[6:7], v[2:3]
	v_lshlrev_b32_e32 v6, 16, v24
	v_and_b32_e32 v7, 0xffff0000, v24
	v_pk_fma_f32 v[2:3], v[26:27], v[6:7], v[2:3]
	v_pk_mul_f32 v[12:13], v[12:13], v[88:89] op_sel_hi:[1,0]
	v_mul_f32_e32 v4, 0xbfb8aa3b, v3
	v_exp_f32_e32 v4, v4
	v_mul_f32_e32 v6, 0xbfb8aa3b, v2
	v_exp_f32_e32 v8, v6
	ds_write_b128 v153, v[12:15] offset:52256
	v_add_f32_e32 v4, 1.0, v4
	v_rcp_f32_e32 v13, v4
	v_lshlrev_b32_e32 v4, 16, v5
	v_and_b32_e32 v5, 0xffff0000, v5
	v_pk_mul_f32 v[6:7], v[10:11], v[44:45] op_sel_hi:[0,1]
	v_add_f32_e32 v11, 1.0, v8
	v_pk_fma_f32 v[4:5], v[72:73], v[4:5], 0 op_sel_hi:[1,1,0]
	v_lshlrev_b32_e32 v8, 16, v9
	v_and_b32_e32 v9, 0xffff0000, v9
	v_pk_fma_f32 v[4:5], v[76:77], v[8:9], v[4:5]
	v_lshlrev_b32_e32 v8, 16, v21
	v_and_b32_e32 v9, 0xffff0000, v21
	v_pk_fma_f32 v[4:5], v[78:79], v[8:9], v[4:5]
	v_lshlrev_b32_e32 v8, 16, v25
	v_and_b32_e32 v9, 0xffff0000, v25
	v_pk_fma_f32 v[8:9], v[28:29], v[8:9], v[4:5]
	v_rcp_f32_e32 v12, v11
	v_mul_f32_e32 v4, 0xbfb8aa3b, v9
	v_exp_f32_e32 v4, v4
	v_mul_f32_e32 v5, 0xbfb8aa3b, v8
	v_exp_f32_e32 v5, v5
	v_pk_mul_f32 v[2:3], v[2:3], v[12:13]
	v_add_f32_e32 v4, 1.0, v4
	v_rcp_f32_e32 v15, v4
	v_add_f32_e32 v4, 1.0, v5
	v_rcp_f32_e32 v14, v4
	v_pk_mul_f32 v[4:5], v[10:11], v[48:49] op_sel_hi:[0,1]
	ds_write_b128 v153, v[4:7] offset:52768
	v_pk_mul_f32 v[2:3], v[2:3], v[88:89] op_sel_hi:[1,0]
	v_pk_mul_f32 v[4:5], v[8:9], v[14:15]
	v_lshl_add_u64 v[18:19], s[10:11], 0, v[18:19]
	v_pk_mul_f32 v[4:5], v[4:5], v[88:89] op_sel_hi:[1,0]
	ds_write_b128 v153, v[2:5] offset:52272
	v_pk_mul_f32 v[4:5], v[10:11], v[42:43] op_sel_hi:[0,1]
	v_pk_mul_f32 v[2:3], v[10:11], v[46:47] op_sel_hi:[0,1]
	ds_write_b128 v153, v[2:5] offset:52784
	v_pk_mul_f32 v[2:3], v[74:75], v[80:81] op_sel_hi:[1,0]
	v_pk_mul_f32 v[4:5], v[70:71], v[80:81] op_sel_hi:[1,0]
	v_pk_mul_f32 v[6:7], v[66:67], v[80:81] op_sel_hi:[1,0]
	v_pk_mul_f32 v[8:9], v[62:63], v[80:81] op_sel_hi:[1,0]
	v_lshl_add_u64 v[18:19], v[18:19], 0, s[88:89]
	v_pk_mul_f32 v[10:11], v[58:59], v[80:81] op_sel_hi:[1,0]
	v_pk_mul_f32 v[12:13], v[68:69], v[80:81] op_sel_hi:[1,0]
	v_pk_mul_f32 v[14:15], v[64:65], v[80:81] op_sel_hi:[1,0]
	v_pk_mul_f32 v[16:17], v[60:61], v[80:81] op_sel_hi:[1,0]
	v_lshl_add_u64 v[18:19], v[18:19], 0, v[0:1]
	v_cvt_pk_bf16_f32 v2, v2, v3
	v_cvt_pk_bf16_f32 v3, v4, v5
	v_cvt_pk_bf16_f32 v4, v6, v7
	v_cvt_pk_bf16_f32 v5, v8, v9
	global_store_dwordx4 v[18:19], v[2:5], off
	v_sub_f32_e32 v69, v89, v81
	s_nop 0
	v_cvt_pk_bf16_f32 v2, v10, v11
	v_cvt_pk_bf16_f32 v3, v12, v13
	v_cvt_pk_bf16_f32 v4, v14, v15
	v_cvt_pk_bf16_f32 v5, v16, v17
	global_store_dwordx4 v[18:19], v[2:5], off offset:16
	s_waitcnt lgkmcnt(0)
	s_barrier
; __device__ __forceinline__ unsigned short bf16_1(float x) { return (unsigned short)(cvt_pk_bf16(x, 0.f) & 0xffffu); }
; __device__ __forceinline__ void gdn_prep(KA a, int layer, unsigned char* lds, const int tid_, const int bid_) {
;     ...
;         {
;             const int fr = lane & 15, fq = lane >> 4, ti = wave >> 1, tj0 = (wave & 1) * 2;
;             bf16x8 Ak[4], Aq[4];
; #pragma unroll
;             for (int ks = 0; ks < 4; ++ks) { Ak[ks] = *(const bf16x8*)(Kb + (16 * ti + fr) * 272 + (32 * ks + 8 * fq) * 2); Aq[ks] = *(const bf16x8*)(Qb + (16 * ti + fr) * 272 + (32 * ks + 8 * fq) * 2); }
; #pragma unroll
;             for (int jj = 0; jj < 2; ++jj) {
;                 const int tj = tj0 + jj;
;                 f32x4 ckk = (f32x4){0.f, 0.f, 0.f, 0.f}, cqk = (f32x4){0.f, 0.f, 0.f, 0.f};
; #pragma unroll
;                 for (int ks = 0; ks < 4; ++ks) { const bf16x8 B = *(const bf16x8*)(Kb + (16 * tj + fr) * 272 + (32 * ks + 8 * fq) * 2);
;                     ckk = __builtin_amdgcn_mfma_f32_16x16x32_bf16(Ak[ks], B, ckk, 0, 0, 0); cqk = __builtin_amdgcn_mfma_f32_16x16x32_bf16(Aq[ks], B, cqk, 0, 0, 0); }
;                 const int jc = 16 * tj + fr; const float gj = gcs[jc];
; #pragma unroll
;                 for (int j = 0; j < 4; ++j) { const int i = 16 * ti + 4 * fq + j; const float gi = gcs[i], bti = bts[i];
;                     const float e = __expf(i >= jc ? gi - gj : 0.f);
;                     Ls[i * 68 + jc] = (i > jc) ? bti * ckk[j] * e : 0.f;
;                     ((bf16_t*)QKs)[i * 72 + jc] = bf16_1((i >= jc) ? cqk[j] * e : 0.f); }
;             }
;         }
	ds_read_b128 v[2:5], v171
	ds_read_b128 v[6:9], v171 offset:17408
	ds_read_b128 v[10:13], v172
	ds_read_b32 v66, v159
	ds_read_b128 v[14:17], v171 offset:17600
	s_waitcnt lgkmcnt(2)
	v_mfma_f32_16x16x32_bf16 v[18:21], v[2:5], v[10:13], 0
	ds_read_b128 v[22:25], v171 offset:64
	ds_read_b128 v[26:29], v171 offset:192
	ds_read_b128 v[30:33], v172 offset:64
	ds_read_b128 v[34:37], v171 offset:128
	ds_read_b128 v[38:41], v172 offset:128
	ds_read_b128 v[58:61], v171 offset:17472
	ds_read_b128 v[62:65], v171 offset:17536
	v_mfma_f32_16x16x32_bf16 v[10:13], v[6:9], v[10:13], 0
	ds_read_b32 v67, v158
	ds_read_b32 v68, v156
	s_waitcnt lgkmcnt(6)
	v_mfma_f32_16x16x32_bf16 v[18:21], v[22:25], v[30:33], v[18:21]
	s_waitcnt lgkmcnt(3)
	v_mfma_f32_16x16x32_bf16 v[10:13], v[58:61], v[30:33], v[10:13]
	ds_read_b128 v[30:33], v172 offset:192
	v_mfma_f32_16x16x32_bf16 v[18:21], v[34:37], v[38:41], v[18:21]
	s_waitcnt lgkmcnt(3)
	v_mfma_f32_16x16x32_bf16 v[10:13], v[62:65], v[38:41], v[10:13]
	s_waitcnt lgkmcnt(1)
	v_sub_f32_e32 v38, v68, v67
	v_mul_f32_e32 v38, 0x3fb8aa3b, v38
	v_cndmask_b32_e64 v38, v38, 0, s[60:61]
	s_waitcnt lgkmcnt(0)
	v_mfma_f32_16x16x32_bf16 v[18:21], v[26:29], v[30:33], v[18:21]
	v_exp_f32_e32 v38, v38
	v_mul_f32_e32 v39, 0x3fb8aa3b, v69
	v_exp_f32_e32 v39, v39
	v_mfma_f32_16x16x32_bf16 v[10:13], v[14:17], v[30:33], v[10:13]
	v_mul_f32_e32 v31, v39, v57
	s_nop 2
	v_mul_f32_e32 v18, v18, v66
	v_mul_f32_e32 v18, v18, v38
	v_cndmask_b32_e64 v18, 0, v18, s[62:63]
	ds_write_b32 v173, v18 offset:34816
	ds_read_b32 v18, v160
	ds_read_b32 v30, v161
	v_mul_f32_e32 v10, v10, v38
	v_cvt_pk_bf16_f32 v10, v10, s0
	v_cndmask_b32_e64 v10, v10, 0, s[60:61]
	s_waitcnt lgkmcnt(1)
	v_sub_f32_e32 v18, v18, v67
	v_mul_f32_e32 v18, 0x3fb8aa3b, v18
	v_cndmask_b32_e64 v18, v18, 0, s[64:65]
	v_exp_f32_e32 v18, v18
	s_waitcnt lgkmcnt(0)
	v_mul_f32_e32 v19, v19, v30
	ds_write_b16 v174, v10
	v_mul_f32_e32 v30, v39, v56
	v_mul_f32_e32 v19, v19, v18
	v_cndmask_b32_e64 v19, v19, 0, s[60:61]
	ds_write_b32 v173, v19 offset:35088
	ds_read_b32 v19, v162
	v_mul_f32_e32 v10, v11, v18
	ds_read_b32 v11, v163
	v_cvt_pk_bf16_f32 v10, v10, s0
	v_cndmask_b32_e64 v10, v10, 0, s[64:65]
	s_waitcnt lgkmcnt(1)
	v_sub_f32_e32 v18, v19, v67
	v_mul_f32_e32 v18, 0x3fb8aa3b, v18
	v_cndmask_b32_e64 v18, v18, 0, s[66:67]
	v_exp_f32_e32 v18, v18
	s_waitcnt lgkmcnt(0)
	v_mul_f32_e32 v11, v20, v11
	ds_write_b16 v174, v10 offset:144
	v_mul_f32_e32 v33, v39, v54
	v_mul_f32_e32 v11, v11, v18
	v_cndmask_b32_e64 v11, 0, v11, s[68:69]
	ds_write_b32 v173, v11 offset:35360
	ds_read_b32 v11, v164
	v_mul_f32_e32 v10, v12, v18
	ds_read_b32 v12, v165
	v_cvt_pk_bf16_f32 v10, v10, s0
	v_cndmask_b32_e64 v10, v10, 0, s[66:67]
	s_waitcnt lgkmcnt(1)
	v_sub_f32_e32 v11, v11, v67
	v_mul_f32_e32 v11, 0x3fb8aa3b, v11
	v_cndmask_b32_e64 v11, v11, 0, s[70:71]
	v_exp_f32_e32 v11, v11
	ds_write_b16 v174, v10 offset:288
	s_waitcnt lgkmcnt(1)
	v_mul_f32_e32 v10, v21, v12
	v_mul_f32_e32 v38, v39, v55
	v_mul_f32_e32 v10, v10, v11
	v_cndmask_b32_e64 v10, 0, v10, s[72:73]
	ds_write_b32 v173, v10 offset:35632
	v_mul_f32_e32 v10, v13, v11
	v_cvt_pk_bf16_f32 v10, v10, s0
	v_cndmask_b32_e64 v10, v10, 0, s[70:71]
	ds_write_b16 v174, v10 offset:432
	ds_read_b128 v[10:13], v175
	ds_read_b32 v32, v166
	ds_read_b128 v[18:21], v175 offset:64
	s_waitcnt lgkmcnt(2)
	v_mfma_f32_16x16x32_bf16 v[2:5], v[2:5], v[10:13], 0
	v_mul_f32_e32 v40, v39, v52
	v_mul_f32_e32 v41, v39, v53
	v_mfma_f32_16x16x32_bf16 v[6:9], v[6:9], v[10:13], 0
	ds_read_b128 v[10:13], v175 offset:128
	s_waitcnt lgkmcnt(1)
	v_mfma_f32_16x16x32_bf16 v[2:5], v[22:25], v[18:21], v[2:5]
	ds_read_b32 v25, v156
	v_mul_f32_e32 v22, v39, v50
	v_mul_f32_e32 v23, v39, v51
	v_mfma_f32_16x16x32_bf16 v[6:9], v[58:61], v[18:21], v[6:9]
	v_mul_f32_e32 v24, v39, v48
	s_waitcnt lgkmcnt(0)
	v_sub_f32_e32 v25, v25, v32
	v_mul_f32_e32 v25, 0x3fb8aa3b, v25
	v_mfma_f32_16x16x32_bf16 v[2:5], v[34:37], v[10:13], v[2:5]
	v_cndmask_b32_e64 v25, v25, 0, s[74:75]
	v_exp_f32_e32 v25, v25
	v_mul_f32_e32 v18, v39, v49
	v_mfma_f32_16x16x32_bf16 v[6:9], v[62:65], v[10:13], v[6:9]
	ds_read_b128 v[10:13], v175 offset:192
	ds_read_b32 v35, v159
	v_mul_f32_e32 v19, v39, v44
	v_mul_f32_e32 v20, v39, v45
	s_waitcnt lgkmcnt(1)
	v_mfma_f32_16x16x32_bf16 v[2:5], v[26:29], v[10:13], v[2:5]
	v_mul_f32_e32 v21, v39, v46
	v_mul_f32_e32 v34, v39, v47
	v_mul_f32_e32 v26, v39, v42
	v_mfma_f32_16x16x32_bf16 v[6:9], v[14:17], v[10:13], v[6:9]
	s_waitcnt lgkmcnt(0)
	s_nop 2
	v_mul_f32_e32 v2, v2, v35
	v_mul_f32_e32 v2, v2, v25
	v_cndmask_b32_e64 v2, 0, v2, s[76:77]
	ds_write_b32 v173, v2 offset:34880
	ds_read_b32 v2, v160
	ds_read_b32 v10, v161
	v_mul_f32_e32 v6, v6, v25
	v_cvt_pk_bf16_f32 v6, v6, s0
	v_cndmask_b32_e64 v6, v6, 0, s[74:75]
	s_waitcnt lgkmcnt(1)
	v_sub_f32_e32 v2, v2, v32
	v_mul_f32_e32 v2, 0x3fb8aa3b, v2
	v_cndmask_b32_e64 v2, v2, 0, s[78:79]
	v_exp_f32_e32 v2, v2
	s_waitcnt lgkmcnt(0)
	v_mul_f32_e32 v3, v3, v10
	ds_write_b16 v167, v6
	v_mul_f32_e32 v27, v39, v43
	v_mul_f32_e32 v3, v3, v2
	v_cndmask_b32_e64 v3, v3, 0, s[74:75]
	ds_write_b32 v173, v3 offset:35152
	ds_read_b32 v3, v162
	ds_read_b32 v6, v163
	v_mul_f32_e32 v2, v7, v2
	v_cvt_pk_bf16_f32 v2, v2, s0
	v_cndmask_b32_e64 v2, v2, 0, s[78:79]
	s_waitcnt lgkmcnt(1)
	v_sub_f32_e32 v3, v3, v32
	v_mul_f32_e32 v3, 0x3fb8aa3b, v3
	v_cndmask_b32_e64 v3, v3, 0, s[80:81]
	v_exp_f32_e32 v3, v3
	s_waitcnt lgkmcnt(0)
	v_mul_f32_e32 v4, v4, v6
	ds_write_b16 v168, v2
	v_mul_f32_e32 v4, v4, v3
	v_cndmask_b32_e64 v4, 0, v4, s[82:83]
	ds_write_b32 v173, v4 offset:35424
	ds_read_b32 v4, v164
	v_mul_f32_e32 v2, v8, v3
	ds_read_b32 v3, v165
	v_cvt_pk_bf16_f32 v2, v2, s0
	v_cndmask_b32_e64 v2, v2, 0, s[80:81]
	s_waitcnt lgkmcnt(1)
	v_sub_f32_e32 v4, v4, v32
	v_mul_f32_e32 v4, 0x3fb8aa3b, v4
	v_cndmask_b32_e64 v4, v4, 0, s[84:85]
	v_exp_f32_e32 v4, v4
	ds_write_b16 v169, v2
	s_waitcnt lgkmcnt(1)
	v_mul_f32_e32 v2, v5, v3
	v_mul_f32_e32 v2, v2, v4
	v_cndmask_b32_e64 v2, 0, v2, s[86:87]
	ds_write_b32 v173, v2 offset:35696
	v_mul_f32_e32 v2, v9, v4
	v_cvt_pk_bf16_f32 v2, v2, s0
	v_cndmask_b32_e64 v2, v2, 0, s[84:85]
	ds_write_b16 v170, v2
	v_cvt_pk_bf16_f32 v2, v30, s0
	s_waitcnt lgkmcnt(0)
	s_barrier
; __device__ __forceinline__ unsigned short bf16_1(float x) { return (unsigned short)(cvt_pk_bf16(x, 0.f) & 0xffffu); }
; __device__ __forceinline__ void gdn_prep(KA a, int layer, unsigned char* lds, const int tid_, const int bid_) {
;     ...
;         for (int e = 0; e < 16; ++e) ((bf16_t*)KDTs)[(16 * sub + e) * 72 + ((((tl >> 3) ^ sub) << 3) | (tl & 7))] = bf16_1(qkv[1][e]);
;     ...
;         } else {
;             const int t2 = tid - 256;
; #pragma unroll
;             for (int r = 0; r < 2; ++r) { const int idx = t2 + 256 * r; *(u32x4*)((bf16_t*)(ws + WS_QK) + (size_t)item * 4096 + idx * 8) = *(const u32x4*)(QKs + (idx >> 3) * 144 + (idx & 7) * 16); }
;         }
	ds_write_b16 v176, v2
	v_cvt_pk_bf16_f32 v2, v31, s0
	ds_write_b16 v176, v2 offset:144
	v_cvt_pk_bf16_f32 v2, v33, s0
	ds_write_b16 v176, v2 offset:288
	v_cvt_pk_bf16_f32 v2, v38, s0
	ds_write_b16 v176, v2 offset:432
	v_cvt_pk_bf16_f32 v2, v40, s0
	ds_write_b16 v176, v2 offset:576
	v_cvt_pk_bf16_f32 v2, v41, s0
	ds_write_b16 v176, v2 offset:720
	v_cvt_pk_bf16_f32 v2, v22, s0
	ds_write_b16 v176, v2 offset:864
	v_cvt_pk_bf16_f32 v2, v23, s0
	ds_write_b16 v176, v2 offset:1008
	v_cvt_pk_bf16_f32 v2, v24, s0
	ds_write_b16 v176, v2 offset:1152
	v_cvt_pk_bf16_f32 v2, v18, s0
	ds_write_b16 v176, v2 offset:1296
	v_cvt_pk_bf16_f32 v2, v19, s0
	ds_write_b16 v176, v2 offset:1440
	v_cvt_pk_bf16_f32 v2, v20, s0
	ds_write_b16 v176, v2 offset:1584
	v_cvt_pk_bf16_f32 v2, v21, s0
	ds_write_b16 v176, v2 offset:1728
	v_cvt_pk_bf16_f32 v2, v34, s0
	ds_write_b16 v176, v2 offset:1872
	v_cvt_pk_bf16_f32 v2, v26, s0
	ds_write_b16 v176, v2 offset:2016
	v_cvt_pk_bf16_f32 v2, v27, s0
	ds_write_b16 v176, v2 offset:2160
	s_and_saveexec_b64 s[20:21], s[46:47]
	s_xor_b64 s[90:91], exec, s[20:21]
	s_cbranch_execz .LBB0_221
	s_ashr_i32 s19, s18, 31
	ds_read_b128 v[2:5], v177
	s_lshl_b64 s[20:21], s[18:19], 13
	s_add_u32 s20, s7, s20
	s_addc_u32 s21, s29, s21
	v_lshl_add_u64 v[6:7], v[100:101], 1, s[20:21]
	s_waitcnt lgkmcnt(0)
	global_store_dwordx4 v[6:7], v[2:5], off
	ds_read_b128 v[2:5], v178
	v_lshl_add_u64 v[6:7], v[90:91], 1, s[20:21]
	s_waitcnt lgkmcnt(0)
	global_store_dwordx4 v[6:7], v[2:5], off

; __device__ __forceinline__ unsigned cvt_pk_bf16(float lo, float hi) { f32x2 v = {lo, hi}; bf16x2_t r = __builtin_convertvector(v, bf16x2_t); return __builtin_bit_cast(unsigned, r); }
; __device__ __forceinline__ void phase_a(KA a, int layer, const float* xin, unsigned char* lds, const int tid_, const int bid_) {
;     ...
;         for (int r8 = 0; r8 < 8; ++r8) {
;             const int m = row0 + r8;
;             const f32x4* xr = (const f32x4*)(xin + (size_t)m * D_) + lane;
;             f32x4 v[8]; float ss = 0.f;
; #pragma unroll
;             for (int j = 0; j < 8; ++j) { v[j] = xr[64 * j]; ss += (v[j].x * v[j].x + v[j].y * v[j].y) + (v[j].z * v[j].z + v[j].w * v[j].w); }
;             ss = wave_sum(ss);
;             const float rstd = rsqrtf(ss * (1.0f / D_) + 1e-6f);
;             u32x2* o8 = (u32x2*)(H + (size_t)m * D_) + lane;
; #pragma unroll
;             for (int j = 0; j < 8; ++j) { v[j] = v[j] * rstd * gn[j]; u32x2 w; w.x = cvt_pk_bf16(v[j].x, v[j].y); w.y = cvt_pk_bf16(v[j].z, v[j].w); o8[64 * j] = w; }
;         }
.LBB0_408:
	v_add_u32_e32 v34, s6, v72
	v_ashrrev_i32_e32 v35, 31, v34
	v_lshlrev_b64 v[36:37], 13, v[34:35]
	v_lshlrev_b64 v[34:35], 12, v[34:35]
	v_lshl_add_u64 v[50:51], v[54:55], 0, v[36:37]
	v_lshl_add_u64 v[88:89], v[56:57], 0, v[34:35]
	global_load_dwordx4 v[34:37], v[50:51], off
	global_load_dwordx4 v[38:41], v[50:51], off offset:1024
	global_load_dwordx4 v[42:45], v[50:51], off offset:2048
	global_load_dwordx4 v[46:49], v[50:51], off offset:3072
	v_add_co_u32_e32 v84, vcc, s23, v50
	s_add_i32 s6, s6, 1
	s_nop 0
	v_addc_co_u32_e32 v85, vcc, 0, v51, vcc
	global_load_dwordx4 v[50:53], v[84:85], off
	global_load_dwordx4 v[64:67], v[84:85], off offset:1024
	global_load_dwordx4 v[80:83], v[84:85], off offset:3072
	s_nop 0
	global_load_dwordx4 v[84:87], v[84:85], off offset:2048
	s_cmp_eq_u32 s6, 8
	s_waitcnt vmcnt(7)
	v_mov_b32_e32 v92, v35
	s_waitcnt vmcnt(6)
	v_mov_b32_e32 v93, v39
	v_mov_b32_e32 v96, v37
	v_mov_b32_e32 v97, v41
	v_mov_b32_e32 v90, v34
	v_mov_b32_e32 v91, v38
	v_mov_b32_e32 v94, v36
	v_mov_b32_e32 v95, v40
	s_waitcnt vmcnt(5)
	v_pk_mul_f32 v[98:99], v[44:45], v[44:45]
	v_pk_mul_f32 v[100:101], v[42:43], v[42:43]
	v_pk_mul_f32 v[92:93], v[92:93], v[92:93]
	v_pk_mul_f32 v[96:97], v[96:97], v[96:97]
	v_pk_mov_b32 v[106:107], v[100:101], v[98:99] op_sel:[1,0]
	v_mov_b32_e32 v101, v99
	v_pk_fma_f32 v[90:91], v[90:91], v[90:91], v[92:93]
	v_pk_fma_f32 v[92:93], v[94:95], v[94:95], v[96:97]
	s_waitcnt vmcnt(4)
	v_mul_f32_e32 v102, v47, v47
	v_mul_f32_e32 v104, v49, v49
	v_pk_add_f32 v[94:95], v[106:107], v[100:101]
	v_pk_add_f32 v[90:91], v[90:91], v[92:93]
	s_waitcnt vmcnt(3)
	v_mul_f32_e32 v59, v50, v50
	v_mul_f32_e32 v79, v51, v51
	v_mul_f32_e32 v111, v52, v52
	v_mul_f32_e32 v113, v53, v53
	v_pk_fma_f32 v[98:99], v[46:47], v[46:47], v[102:103] op_sel_hi:[1,1,0]
	v_pk_fma_f32 v[102:103], v[48:49], v[48:49], v[104:105] op_sel_hi:[1,1,0]
	v_pk_add_f32 v[92:93], v[94:95], v[94:95] op_sel:[0,1] op_sel_hi:[1,0]
	v_pk_add_f32 v[90:91], v[90:91], v[90:91] op_sel:[0,1] op_sel_hi:[1,0]
	s_waitcnt vmcnt(2)
	v_pk_mul_f32 v[104:105], v[66:67], v[66:67]
	v_pk_mul_f32 v[108:109], v[64:65], v[64:65]
	v_mov_b32_e32 v99, v111
	v_mov_b32_e32 v103, v113
	v_mov_b32_e32 v93, v79
	v_mov_b32_e32 v91, v59
	v_pk_mov_b32 v[96:97], v[108:109], v[104:105] op_sel:[1,0]
	v_mov_b32_e32 v109, v105
	v_pk_add_f32 v[94:95], v[98:99], v[102:103]
	v_pk_add_f32 v[90:91], v[90:91], v[92:93]
	s_waitcnt vmcnt(0)
	v_mul_f32_e32 v110, v85, v85
	v_mul_f32_e32 v112, v87, v87
	v_pk_add_f32 v[96:97], v[96:97], v[108:109]
	v_pk_add_f32 v[90:91], v[90:91], v[94:95]
	v_mul_f32_e32 v114, v80, v80
	v_mul_f32_e32 v115, v81, v81
	v_mul_f32_e32 v116, v82, v82
	v_mul_f32_e32 v117, v83, v83
	v_pk_fma_f32 v[100:101], v[84:85], v[84:85], v[110:111] op_sel_hi:[1,1,0]
	v_pk_fma_f32 v[104:105], v[86:87], v[86:87], v[112:113] op_sel_hi:[1,1,0]
	v_pk_add_f32 v[96:97], v[96:97], v[96:97] op_sel:[0,1] op_sel_hi:[1,0]
	v_pk_add_f32 v[90:91], v[90:91], v[90:91] op_sel:[0,1] op_sel_hi:[1,0]
	v_mov_b32_e32 v101, v116
	v_mov_b32_e32 v105, v117
	v_mov_b32_e32 v97, v115
	v_mov_b32_e32 v91, v114
	v_pk_add_f32 v[98:99], v[100:101], v[104:105]
	v_pk_add_f32 v[90:91], v[90:91], v[96:97]
	s_nop 0
	v_pk_add_f32 v[90:91], v[90:91], v[98:99]
	s_nop 0
	v_add_f32_e32 v59, v90, v91
	s_nop 1
	v_add_f32_dpp v59, v59, v59 quad_perm:[1,0,3,2] row_mask:0xf bank_mask:0xf
	s_waitcnt lgkmcnt(0)
	s_nop 1
	v_add_f32_dpp v59, v59, v59 quad_perm:[2,3,0,1] row_mask:0xf bank_mask:0xf
	s_waitcnt lgkmcnt(0)
	s_nop 1
	v_add_f32_dpp v59, v59, v59 row_half_mirror row_mask:0xf bank_mask:0xf
	s_waitcnt lgkmcnt(0)
	s_nop 1
	v_add_f32_dpp v59, v59, v59 row_mirror row_mask:0xf bank_mask:0xf
	s_waitcnt lgkmcnt(0)
	ds_bpermute_b32 v79, v77, v59
	s_waitcnt lgkmcnt(0)
	v_add_f32_e32 v59, v59, v79
	ds_bpermute_b32 v79, v78, v59
	s_waitcnt lgkmcnt(0)
	v_add_f32_e32 v59, v59, v79
	v_fmamk_f32 v59, v59, 0x3a000000, v227
	v_mul_f32_e32 v79, 0x4b800000, v59
	v_cmp_gt_f32_e32 vcc, s24, v59
	s_nop 1
	v_cndmask_b32_e32 v59, v59, v79, vcc
	v_rsq_f32_e32 v59, v59
	s_nop 0
	v_mul_f32_e32 v79, 0x45800000, v59
	v_cndmask_b32_e32 v90, v59, v79, vcc
	v_pk_mul_f32 v[34:35], v[34:35], v[90:91] op_sel_hi:[1,0]
	v_pk_mul_f32 v[36:37], v[36:37], v[90:91] op_sel_hi:[1,0]
	v_pk_mul_f32 v[38:39], v[38:39], v[90:91] op_sel_hi:[1,0]
	v_pk_mul_f32 v[40:41], v[40:41], v[90:91] op_sel_hi:[1,0]
	v_pk_mul_f32 v[42:43], v[42:43], v[90:91] op_sel_hi:[1,0]
	v_pk_mul_f32 v[44:45], v[44:45], v[90:91] op_sel_hi:[1,0]
	v_pk_mul_f32 v[46:47], v[46:47], v[90:91] op_sel_hi:[1,0]
	v_pk_mul_f32 v[48:49], v[48:49], v[90:91] op_sel_hi:[1,0]
	v_pk_mul_f32 v[50:51], v[50:51], v[90:91] op_sel_hi:[1,0]
	v_pk_mul_f32 v[52:53], v[52:53], v[90:91] op_sel_hi:[1,0]
	v_pk_mul_f32 v[64:65], v[64:65], v[90:91] op_sel_hi:[1,0]
	v_pk_mul_f32 v[66:67], v[66:67], v[90:91] op_sel_hi:[1,0]
	v_pk_mul_f32 v[84:85], v[84:85], v[90:91] op_sel_hi:[1,0]
	v_pk_mul_f32 v[86:87], v[86:87], v[90:91] op_sel_hi:[1,0]
	v_pk_mul_f32 v[80:81], v[80:81], v[90:91] op_sel_hi:[1,0]
	v_pk_mul_f32 v[82:83], v[82:83], v[90:91] op_sel_hi:[1,0]
	v_pk_mul_f32 v[36:37], v[4:5], v[36:37]
	v_pk_mul_f32 v[34:35], v[2:3], v[34:35]
	v_pk_mul_f32 v[40:41], v[8:9], v[40:41]
	v_pk_mul_f32 v[38:39], v[6:7], v[38:39]
	v_pk_mul_f32 v[44:45], v[12:13], v[44:45]
	v_pk_mul_f32 v[42:43], v[10:11], v[42:43]
	v_pk_mul_f32 v[48:49], v[16:17], v[48:49]
	v_pk_mul_f32 v[46:47], v[14:15], v[46:47]
	v_pk_mul_f32 v[52:53], v[20:21], v[52:53]
	v_pk_mul_f32 v[50:51], v[18:19], v[50:51]
	v_pk_mul_f32 v[66:67], v[24:25], v[66:67]
	v_pk_mul_f32 v[64:65], v[22:23], v[64:65]
	v_pk_mul_f32 v[86:87], v[28:29], v[86:87]
	v_pk_mul_f32 v[84:85], v[26:27], v[84:85]
	v_pk_mul_f32 v[82:83], v[32:33], v[82:83]
	v_pk_mul_f32 v[80:81], v[30:31], v[80:81]
	v_cvt_pk_bf16_f32 v34, v34, v35
	v_cvt_pk_bf16_f32 v35, v36, v37
	v_cvt_pk_bf16_f32 v36, v38, v39
	v_cvt_pk_bf16_f32 v37, v40, v41
	v_cvt_pk_bf16_f32 v38, v42, v43
	v_cvt_pk_bf16_f32 v39, v44, v45
	v_cvt_pk_bf16_f32 v40, v46, v47
	v_cvt_pk_bf16_f32 v41, v48, v49
	v_cvt_pk_bf16_f32 v42, v50, v51
	v_cvt_pk_bf16_f32 v43, v52, v53
	v_cvt_pk_bf16_f32 v44, v64, v65
	v_cvt_pk_bf16_f32 v45, v66, v67
	v_cvt_pk_bf16_f32 v46, v84, v85
	v_cvt_pk_bf16_f32 v47, v86, v87
	v_cvt_pk_bf16_f32 v48, v80, v81
	v_cvt_pk_bf16_f32 v49, v82, v83
	global_store_dwordx2 v[88:89], v[34:35], off
	global_store_dwordx2 v[88:89], v[36:37], off offset:512
	global_store_dwordx2 v[88:89], v[38:39], off offset:1024
	global_store_dwordx2 v[88:89], v[40:41], off offset:1536
	global_store_dwordx2 v[88:89], v[42:43], off offset:2048
	global_store_dwordx2 v[88:89], v[44:45], off offset:2560
	global_store_dwordx2 v[88:89], v[46:47], off offset:3072
	global_store_dwordx2 v[88:89], v[48:49], off offset:3584
	s_cbranch_scc0 .LBB0_408
	v_ashrrev_i32_e32 v59, 31, v58
	v_lshlrev_b64 v[34:35], 12, v[58:59]
	s_waitcnt vmcnt(0)
	v_lshl_add_u64 v[64:65], v[62:63], 0, v[34:35]
	v_mov_b32_e32 v34, 0
	s_mov_b64 s[6:7], 0
	v_mov_b32_e32 v59, v70
	v_mov_b32_e32 v35, v34
	v_mov_b32_e32 v36, v34
	v_mov_b32_e32 v37, v34

; __device__ __forceinline__ void phase_final(KA a, const float* x, const int tid_, const int bid_) {
;     ...
;     for (int m = gw; m < T_; m += NGW) {
;         const f32x4* xr = (const f32x4*)(x + (size_t)m * D_) + lane;
;         f32x4 v[8]; float ss = 0.f;
; #pragma unroll
;         for (int j = 0; j < 8; ++j) { v[j] = xr[64 * j]; ss += (v[j].x * v[j].x + v[j].y * v[j].y) + (v[j].z * v[j].z + v[j].w * v[j].w); }
;         ss = wave_sum(ss);
;         const float rstd = rsqrtf(ss * (1.0f / D_) + 1e-6f);
;         f32x4* o = (f32x4*)(a->out + (size_t)m * D_) + lane;
; #pragma unroll
;         for (int j = 0; j < 8; ++j) o[64 * j] = v[j] * rstd * gn[j];
;     }
.LBB0_440:
	global_load_dwordx4 v[34:37], v[66:67], off offset:-2048
	global_load_dwordx4 v[38:41], v[66:67], off
	global_load_dwordx4 v[42:45], v[66:67], off offset:-1024
	v_add_co_u32_e32 v68, vcc, 0xfffff000, v66
	v_add_u32_e32 v72, s2, v72
	s_nop 0
	v_addc_co_u32_e32 v69, vcc, -1, v67, vcc
	global_load_dwordx4 v[50:53], v[68:69], off offset:-1024
	global_load_dwordx4 v[46:49], v[66:67], off offset:-4096
	global_load_dwordx4 v[58:61], v[68:69], off offset:-3072
	global_load_dwordx4 v[54:57], v[68:69], off offset:-2048
	global_load_dwordx4 v[62:65], v[66:67], off offset:-3072
	s_waitcnt vmcnt(3)
	v_pk_mul_f32 v[100:101], v[36:37], v[36:37]
	v_pk_mul_f32 v[102:103], v[34:35], v[34:35]
	v_mul_f32_e32 v0, v43, v43
	v_mul_f32_e32 v104, v45, v45
	v_mul_f32_e32 v70, v40, v40
	v_mul_f32_e32 v71, v41, v41
	v_pk_mov_b32 v[106:107], v[102:103], v[100:101] op_sel:[1,0]
	v_mov_b32_e32 v103, v101
	v_pk_fma_f32 v[100:101], v[42:43], v[42:43], v[0:1] op_sel_hi:[1,1,0]
	v_pk_fma_f32 v[104:105], v[44:45], v[44:45], v[104:105] op_sel_hi:[1,1,0]
	v_mov_b32_e32 v101, v70
	v_mov_b32_e32 v105, v71
	v_pk_add_f32 v[80:81], v[106:107], v[102:103]
	v_pk_add_f32 v[70:71], v[100:101], v[104:105]
	v_pk_mul_f32 v[108:109], v[52:53], v[52:53]
	v_pk_mul_f32 v[110:111], v[50:51], v[50:51]
	v_mul_f32_e32 v0, v47, v47
	v_pk_mov_b32 v[82:83], v[110:111], v[108:109] op_sel:[1,0]
	v_mov_b32_e32 v111, v109
	v_pk_add_f32 v[82:83], v[82:83], v[110:111]
	v_pk_add_f32 v[80:81], v[80:81], v[80:81] op_sel:[0,1] op_sel_hi:[1,0]
	v_pk_add_f32 v[82:83], v[82:83], v[82:83] op_sel:[0,1] op_sel_hi:[1,0]
	v_mul_f32_e32 v81, v39, v39
	s_waitcnt vmcnt(2)
	v_mov_b32_e32 v84, v59
	s_waitcnt vmcnt(1)
	v_mov_b32_e32 v85, v55
	v_mov_b32_e32 v108, v58
	v_mov_b32_e32 v109, v54
	v_pk_mul_f32 v[84:85], v[84:85], v[84:85]
	v_mov_b32_e32 v86, v61
	v_mov_b32_e32 v87, v57
	v_pk_fma_f32 v[108:109], v[108:109], v[108:109], v[84:85]
	v_mov_b32_e32 v84, v60
	v_mov_b32_e32 v85, v56
	v_pk_mul_f32 v[86:87], v[86:87], v[86:87]
	s_nop 0
	v_pk_fma_f32 v[84:85], v[84:85], v[84:85], v[86:87]
	v_pk_fma_f32 v[86:87], v[46:47], v[46:47], v[0:1] op_sel_hi:[1,1,0]
	v_pk_add_f32 v[84:85], v[108:109], v[84:85]
	v_mul_f32_e32 v0, v49, v49
	v_pk_fma_f32 v[88:89], v[48:49], v[48:49], v[0:1] op_sel_hi:[1,1,0]
	v_pk_add_f32 v[84:85], v[84:85], v[84:85] op_sel:[0,1] op_sel_hi:[1,0]
	s_waitcnt vmcnt(0)
	v_mul_f32_e32 v87, v64, v64
	v_mul_f32_e32 v89, v65, v65
	v_mul_f32_e32 v83, v63, v63
	v_mul_f32_e32 v85, v62, v62
	v_pk_add_f32 v[86:87], v[86:87], v[88:89]
	v_pk_add_f32 v[82:83], v[84:85], v[82:83]
	s_nop 0
	v_pk_add_f32 v[82:83], v[82:83], v[86:87]
	s_nop 0
	v_pk_add_f32 v[82:83], v[82:83], v[82:83] op_sel:[0,1] op_sel_hi:[1,0]
	s_nop 0
	v_mul_f32_e32 v83, v38, v38
	v_pk_add_f32 v[80:81], v[82:83], v[80:81]
	s_nop 0
	v_pk_add_f32 v[70:71], v[80:81], v[70:71]
	s_nop 0
	v_add_f32_e32 v0, v70, v71
	s_nop 1
	v_add_f32_dpp v0, v0, v0 quad_perm:[1,0,3,2] row_mask:0xf bank_mask:0xf
	s_waitcnt lgkmcnt(0)
	s_nop 1
	v_add_f32_dpp v0, v0, v0 quad_perm:[2,3,0,1] row_mask:0xf bank_mask:0xf
	s_waitcnt lgkmcnt(0)
	s_nop 1
	v_add_f32_dpp v0, v0, v0 row_half_mirror row_mask:0xf bank_mask:0xf
	s_waitcnt lgkmcnt(0)
	s_nop 1
	v_add_f32_dpp v0, v0, v0 row_mirror row_mask:0xf bank_mask:0xf
	s_waitcnt lgkmcnt(0)
	ds_bpermute_b32 v70, v77, v0
	s_waitcnt lgkmcnt(0)
	v_add_f32_e32 v0, v0, v70
	ds_bpermute_b32 v70, v78, v0
	s_waitcnt lgkmcnt(0)
	v_add_f32_e32 v0, v0, v70
	v_fmamk_f32 v0, v0, 0x3a000000, v227
	v_mul_f32_e32 v70, 0x4b800000, v0
	v_cmp_gt_f32_e32 vcc, s24, v0
	s_nop 1
	v_cndmask_b32_e32 v0, v0, v70, vcc
	v_rsq_f32_e32 v0, v0
	s_nop 0
	v_mul_f32_e32 v70, 0x45800000, v0
	v_cndmask_b32_e32 v0, v0, v70, vcc
	v_pk_mul_f32 v[58:59], v[58:59], v[0:1] op_sel_hi:[1,0]
	v_pk_mul_f32 v[60:61], v[60:61], v[0:1] op_sel_hi:[1,0]
	v_pk_mul_f32 v[54:55], v[54:55], v[0:1] op_sel_hi:[1,0]
	v_pk_mul_f32 v[56:57], v[56:57], v[0:1] op_sel_hi:[1,0]
	v_pk_mul_f32 v[50:51], v[50:51], v[0:1] op_sel_hi:[1,0]
	v_pk_mul_f32 v[52:53], v[52:53], v[0:1] op_sel_hi:[1,0]
	v_pk_mul_f32 v[46:47], v[46:47], v[0:1] op_sel_hi:[1,0]
	v_pk_mul_f32 v[48:49], v[48:49], v[0:1] op_sel_hi:[1,0]
	v_pk_mul_f32 v[62:63], v[62:63], v[0:1] op_sel_hi:[1,0]
	v_pk_mul_f32 v[64:65], v[64:65], v[0:1] op_sel_hi:[1,0]
	v_pk_mul_f32 v[70:71], v[34:35], v[0:1] op_sel_hi:[1,0]
	v_pk_mul_f32 v[80:81], v[36:37], v[0:1] op_sel_hi:[1,0]
	v_pk_mul_f32 v[82:83], v[42:43], v[0:1] op_sel_hi:[1,0]
	v_pk_mul_f32 v[84:85], v[44:45], v[0:1] op_sel_hi:[1,0]
	v_pk_mul_f32 v[86:87], v[38:39], v[0:1] op_sel_hi:[1,0]
	v_pk_mul_f32 v[88:89], v[40:41], v[0:1] op_sel_hi:[1,0]
	v_pk_mul_f32 v[36:37], v[4:5], v[60:61]
	v_pk_mul_f32 v[34:35], v[2:3], v[58:59]
	v_cmp_lt_i32_e32 vcc, s22, v72
	v_pk_mul_f32 v[40:41], v[8:9], v[56:57]
	v_pk_mul_f32 v[38:39], v[6:7], v[54:55]
	v_pk_mul_f32 v[44:45], v[12:13], v[52:53]
	v_pk_mul_f32 v[42:43], v[10:11], v[50:51]
	v_pk_mul_f32 v[48:49], v[16:17], v[48:49]
	v_pk_mul_f32 v[46:47], v[14:15], v[46:47]
	v_pk_mul_f32 v[52:53], v[20:21], v[64:65]
	v_pk_mul_f32 v[50:51], v[18:19], v[62:63]
	v_pk_mul_f32 v[56:57], v[24:25], v[80:81]
	v_pk_mul_f32 v[54:55], v[22:23], v[70:71]
	v_pk_mul_f32 v[60:61], v[28:29], v[84:85]
	v_pk_mul_f32 v[58:59], v[26:27], v[82:83]
	v_pk_mul_f32 v[64:65], v[32:33], v[88:89]
	v_pk_mul_f32 v[62:63], v[30:31], v[86:87]
	s_or_b64 s[8:9], vcc, s[8:9]
	global_store_dwordx4 v[68:69], v[34:37], off offset:-3072
	global_store_dwordx4 v[68:69], v[38:41], off offset:-2048
	global_store_dwordx4 v[68:69], v[42:45], off offset:-1024
	global_store_dwordx4 v[66:67], v[46:49], off offset:-4096
	global_store_dwordx4 v[66:67], v[50:53], off offset:-3072
	global_store_dwordx4 v[66:67], v[54:57], off offset:-2048
	global_store_dwordx4 v[66:67], v[58:61], off offset:-1024
	global_store_dwordx4 v[66:67], v[62:65], off
	v_lshl_add_u64 v[66:67], v[66:67], 0, s[6:7]
	s_andn2_b64 exec, exec, s[8:9]
	s_cbranch_execnz .LBB0_440
